# p13 + O4/E5/M2F (residual epilogues): same ds_bpermute lane transpose of the bf16 stream stores, borrowing v244-v249 (restored at the phase exits)
# baseline (speedup 1.0000x reference)
.LBB0_151:
	s_or_b64 exec, exec, s[0:1]
	s_waitcnt lgkmcnt(0)
	s_barrier
	v_mov_b32_e32 v244, 0xbab64f3b
	v_not_b32_e32 v245, 31
	v_mov_b32_e32 v246, 0x7fc00000
	v_mov_b32_e32 v247, 0x7f800000
	v_mov_b32_e32 v248, 0xff61b1e6
	v_mov_b32_e32 v249, 0x3c0881c4

.LBB0_423:
	v_mbcnt_lo_u32_b32 v255, -1, 0
	v_mbcnt_hi_u32_b32 v255, -1, v255
	v_lshrrev_b32_e32 v244, 2, v255
	v_and_b32_e32 v245, 3, v255
	v_and_b32_e32 v246, 15, v255
	v_lshrrev_b32_e32 v247, 4, v255
	v_sub_u32_e32 v246, v244, v246
	v_sub_u32_e32 v247, v245, v247
	v_mul_i32_i24_e32 v246, 0x1000, v246
	v_lshl_add_u32 v248, v247, 4, v246
	v_ashrrev_i32_e32 v249, 31, v248
	v_lshl_add_u32 v255, v245, 4, v244
	v_lshlrev_b32_e32 v255, 2, v255
	v_lshl_or_b32 v216, s14, 8, v250
	v_lshl_add_u32 v232, s16, 8, v238
	v_ashrrev_i32_e32 v217, 31, v216
	v_lshlrev_b64 v[234:235], 1, v[216:217]
	v_ashrrev_i32_e32 v233, 31, v232
	v_lshl_add_u64 v[134:135], v[202:203], 0, v[234:235]
	v_lshlrev_b64 v[236:237], 12, v[232:233]
	v_lshl_add_u64 v[130:131], v[134:135], 0, v[236:237]
	global_load_dwordx4 v[190:193], v[130:131], off
	global_load_dwordx4 v[186:189], v[130:131], off offset:256
	v_or_b32_e32 v230, 16, v232
	v_ashrrev_i32_e32 v231, 31, v230
	v_lshlrev_b64 v[130:131], 12, v[230:231]
	v_or_b32_e32 v228, 32, v232
	v_lshl_add_u64 v[130:131], v[134:135], 0, v[130:131]
	v_ashrrev_i32_e32 v229, 31, v228
	global_load_dwordx4 v[182:185], v[130:131], off
	global_load_dwordx4 v[178:181], v[130:131], off offset:256
	v_lshlrev_b64 v[130:131], 12, v[228:229]
	v_or_b32_e32 v226, 48, v232
	v_lshl_add_u64 v[130:131], v[134:135], 0, v[130:131]
	v_ashrrev_i32_e32 v227, 31, v226
	global_load_dwordx4 v[174:177], v[130:131], off
	global_load_dwordx4 v[170:173], v[130:131], off offset:256
	v_lshlrev_b64 v[130:131], 12, v[226:227]
	v_add_u32_e32 v224, 0x80, v232
	v_lshl_add_u64 v[130:131], v[134:135], 0, v[130:131]
	v_ashrrev_i32_e32 v225, 31, v224
	global_load_dwordx4 v[166:169], v[130:131], off
	global_load_dwordx4 v[162:165], v[130:131], off offset:256
	v_lshlrev_b64 v[130:131], 12, v[224:225]
	v_add_u32_e32 v222, 0x90, v232
	v_lshl_add_u64 v[130:131], v[134:135], 0, v[130:131]
	v_ashrrev_i32_e32 v223, 31, v222
	global_load_dwordx4 v[158:161], v[130:131], off
	global_load_dwordx4 v[154:157], v[130:131], off offset:256
	v_lshlrev_b64 v[130:131], 12, v[222:223]
	v_add_u32_e32 v220, 0xa0, v232
	v_add_u32_e32 v218, 0xb0, v232
	v_lshl_add_u64 v[130:131], v[134:135], 0, v[130:131]
	v_ashrrev_i32_e32 v221, 31, v220
	v_ashrrev_i32_e32 v219, 31, v218
	global_load_dwordx4 v[150:153], v[130:131], off
	global_load_dwordx4 v[146:149], v[130:131], off offset:256
	v_lshlrev_b64 v[130:131], 12, v[220:221]
	v_lshlrev_b64 v[136:137], 12, v[218:219]
	v_lshl_add_u64 v[130:131], v[134:135], 0, v[130:131]
	v_lshl_add_u64 v[134:135], v[134:135], 0, v[136:137]
	global_load_dwordx4 v[138:141], v[130:131], off
	s_nop 0
	global_load_dwordx4 v[130:133], v[130:131], off offset:256
	s_nop 0
	global_load_dwordx4 v[142:145], v[134:135], off
	s_nop 0
	global_load_dwordx4 v[134:137], v[134:135], off offset:256
	s_mov_b64 vcc, s[2:3]
	s_cbranch_vccz .Lalign_skip_3
	s_barrier
.Lalign_skip_3:
	s_lshl_b32 s14, s14, 2
	s_ashr_i32 s15, s14, 31
	s_waitcnt vmcnt(0)
	v_lshlrev_b32_e32 v206, 16, v190
	v_and_b32_e32 v207, 0xffff0000, v190
	v_lshlrev_b32_e32 v190, 16, v191
	v_and_b32_e32 v191, 0xffff0000, v191
	v_pk_add_f32 v[124:125], v[124:125], v[190:191]
	v_pk_add_f32 v[122:123], v[122:123], v[206:207]
	v_lshlrev_b32_e32 v252, 16, v192
	v_and_b32_e32 v253, 0xffff0000, v192
	v_mul_f32_e32 v0, v123, v123
	v_mul_f32_e32 v190, v125, v125
	v_pk_add_f32 v[126:127], v[126:127], v[252:253]
	v_fmac_f32_e32 v0, v122, v122
	v_fmac_f32_e32 v190, v124, v124
	v_add_f32_e32 v0, v0, v190
	v_mul_f32_e32 v190, v127, v127
	v_lshlrev_b32_e32 v192, 16, v193
	v_and_b32_e32 v193, 0xffff0000, v193
	v_fmac_f32_e32 v190, v126, v126
	v_cvt_pk_bf16_f32 v122, v122, v123
	v_cvt_pk_bf16_f32 v123, v124, v125
	v_cvt_pk_bf16_f32 v124, v126, v127
	v_lshl_add_u64 v[126:127], v[202:203], 0, v[236:237]
	v_pk_add_f32 v[128:129], v[128:129], v[192:193]
	v_lshl_add_u64 v[126:127], v[126:127], 0, v[234:235]
	v_cvt_pk_bf16_f32 v125, v128, v129
	v_mul_f32_e32 v191, v129, v129
	ds_bpermute_b32 v244, v255, v122
	ds_bpermute_b32 v245, v255, v123
	ds_bpermute_b32 v246, v255, v124
	ds_bpermute_b32 v247, v255, v125
	v_fmac_f32_e32 v191, v128, v128
	v_lshlrev_b32_e32 v128, 16, v188
	v_lshlrev_b32_e32 v122, 16, v186
	v_and_b32_e32 v123, 0xffff0000, v186
	v_lshlrev_b32_e32 v124, 16, v187
	v_and_b32_e32 v125, 0xffff0000, v187
	v_and_b32_e32 v129, 0xffff0000, v188
	v_lshlrev_b32_e32 v186, 16, v189
	v_and_b32_e32 v187, 0xffff0000, v189
	v_pk_add_f32 v[120:121], v[120:121], v[124:125]
	v_pk_add_f32 v[118:119], v[118:119], v[122:123]
	v_pk_add_f32 v[122:123], v[116:117], v[186:187]
	v_pk_add_f32 v[116:117], v[114:115], v[128:129]
	v_mul_f32_e32 v114, v119, v119
	v_mul_f32_e32 v115, v121, v121
	v_fmac_f32_e32 v114, v118, v118
	v_fmac_f32_e32 v115, v120, v120
	v_add_f32_e32 v114, v114, v115
	v_mul_f32_e32 v115, v117, v117
	v_mul_f32_e32 v124, v123, v123
	v_fmac_f32_e32 v115, v116, v116
	v_fmac_f32_e32 v124, v122, v122
	v_add_f32_e32 v190, v190, v191
	v_add_f32_e32 v115, v115, v124
	v_add_f32_e32 v0, v0, v190
	v_add_f32_e32 v114, v114, v115
	v_add_f32_e32 v0, v0, v114
	v_cvt_pk_bf16_f32 v114, v118, v119
	v_cvt_pk_bf16_f32 v115, v120, v121
	v_cvt_pk_bf16_f32 v116, v116, v117
	v_cvt_pk_bf16_f32 v117, v122, v123
	ds_bpermute_b32 v114, v255, v114
	ds_bpermute_b32 v115, v255, v115
	ds_bpermute_b32 v116, v255, v116
	ds_bpermute_b32 v117, v255, v117
	v_lshl_add_u64 v[126:127], v[126:127], 0, v[248:249]
	s_waitcnt lgkmcnt(4)
	global_store_dwordx4 v[126:127], v[244:247], off
	s_waitcnt lgkmcnt(0)
	global_store_dwordx4 v[126:127], v[114:117], off offset:256
	s_nop 1
	v_mov_b32_e32 v114, v0
	s_nop 1
	v_permlane16_swap_b32_e32 v0, v114
	v_add_f32_e32 v0, v0, v114
	v_mov_b32_e32 v114, v0
	s_nop 1
	v_permlane32_swap_b32_e32 v0, v114
	s_and_saveexec_b64 s[16:17], s[6:7]
	s_cbranch_execz .LBB0_425
	v_lshlrev_b64 v[116:117], 6, v[232:233]
	v_lshl_add_u64 v[116:117], v[204:205], 0, v[116:117]
	v_lshl_add_u64 v[116:117], s[14:15], 1, v[116:117]
	s_lshl_b32 s18, s29, 1
	s_mov_b32 s19, s40
	v_lshl_add_u64 v[116:117], v[116:117], 0, s[18:19]
	v_add_f32_e32 v0, v0, v114
	v_cvt_pk_bf16_f32 v0, v0, v1
	global_store_short v[116:117], v0, off
.LBB0_425:
	s_or_b64 exec, exec, s[16:17]
	v_lshlrev_b32_e32 v116, 16, v182
	v_and_b32_e32 v117, 0xffff0000, v182
	v_lshlrev_b32_e32 v118, 16, v183
	v_and_b32_e32 v119, 0xffff0000, v183
	v_lshlrev_b32_e32 v120, 16, v184
	v_and_b32_e32 v121, 0xffff0000, v184
	v_lshlrev_b32_e32 v122, 16, v185
	v_and_b32_e32 v123, 0xffff0000, v185
	v_pk_add_f32 v[112:113], v[112:113], v[118:119]
	v_pk_add_f32 v[110:111], v[110:111], v[116:117]
	v_pk_add_f32 v[116:117], v[108:109], v[122:123]
	v_pk_add_f32 v[108:109], v[106:107], v[120:121]
	v_mul_f32_e32 v0, v111, v111
	v_mul_f32_e32 v106, v113, v113
	v_fmac_f32_e32 v0, v110, v110
	v_fmac_f32_e32 v106, v112, v112
	v_add_f32_e32 v0, v0, v106
	v_mul_f32_e32 v106, v109, v109
	v_mul_f32_e32 v107, v117, v117
	v_fmac_f32_e32 v106, v108, v108
	v_fmac_f32_e32 v107, v116, v116
	v_lshlrev_b64 v[114:115], 11, v[230:231]
	v_add_f32_e32 v106, v106, v107
	v_add_f32_e32 v0, v0, v106
	v_cvt_pk_bf16_f32 v106, v110, v111
	v_lshl_add_u64 v[110:111], v[114:115], 1, v[202:203]
	v_cvt_pk_bf16_f32 v107, v112, v113
	v_cvt_pk_bf16_f32 v108, v108, v109
	v_cvt_pk_bf16_f32 v109, v116, v117
	v_lshl_add_u64 v[110:111], v[216:217], 1, v[110:111]
	ds_bpermute_b32 v244, v255, v106
	ds_bpermute_b32 v245, v255, v107
	ds_bpermute_b32 v246, v255, v108
	ds_bpermute_b32 v247, v255, v109
	v_lshlrev_b32_e32 v112, 16, v180
	v_and_b32_e32 v113, 0xffff0000, v180
	v_lshlrev_b32_e32 v106, 16, v178
	v_and_b32_e32 v107, 0xffff0000, v178
	v_lshlrev_b32_e32 v108, 16, v179
	v_and_b32_e32 v109, 0xffff0000, v179
	v_lshlrev_b32_e32 v114, 16, v181
	v_and_b32_e32 v115, 0xffff0000, v181
	v_pk_add_f32 v[104:105], v[104:105], v[108:109]
	v_pk_add_f32 v[102:103], v[102:103], v[106:107]
	v_pk_add_f32 v[106:107], v[100:101], v[114:115]
	v_pk_add_f32 v[100:101], v[98:99], v[112:113]
	v_mul_f32_e32 v98, v103, v103
	v_mul_f32_e32 v99, v105, v105
	v_fmac_f32_e32 v98, v102, v102
	v_fmac_f32_e32 v99, v104, v104
	v_add_f32_e32 v98, v98, v99
	v_mul_f32_e32 v99, v101, v101
	v_mul_f32_e32 v108, v107, v107
	v_fmac_f32_e32 v99, v100, v100
	v_fmac_f32_e32 v108, v106, v106
	v_add_f32_e32 v99, v99, v108
	v_add_f32_e32 v98, v98, v99
	v_add_f32_e32 v0, v0, v98
	v_cvt_pk_bf16_f32 v98, v102, v103
	v_cvt_pk_bf16_f32 v99, v104, v105
	v_cvt_pk_bf16_f32 v100, v100, v101
	v_cvt_pk_bf16_f32 v101, v106, v107
	ds_bpermute_b32 v98, v255, v98
	ds_bpermute_b32 v99, v255, v99
	ds_bpermute_b32 v100, v255, v100
	ds_bpermute_b32 v101, v255, v101
	v_lshl_add_u64 v[110:111], v[110:111], 0, v[248:249]
	s_waitcnt lgkmcnt(4)
	global_store_dwordx4 v[110:111], v[244:247], off
	s_waitcnt lgkmcnt(0)
	global_store_dwordx4 v[110:111], v[98:101], off offset:256
	s_nop 1
	v_mov_b32_e32 v98, v0
	s_nop 1
	v_permlane16_swap_b32_e32 v0, v98
	v_add_f32_e32 v0, v0, v98
	v_mov_b32_e32 v98, v0
	s_nop 1
	v_permlane32_swap_b32_e32 v0, v98
	s_and_saveexec_b64 s[16:17], s[6:7]
	s_cbranch_execz .LBB0_427
	v_lshlrev_b64 v[100:101], 6, v[230:231]
	v_lshl_add_u64 v[100:101], v[204:205], 0, v[100:101]
	v_lshl_add_u64 v[100:101], s[14:15], 1, v[100:101]
	s_lshl_b32 s18, s29, 1
	s_mov_b32 s19, s40
	v_lshl_add_u64 v[100:101], v[100:101], 0, s[18:19]
	v_add_f32_e32 v0, v0, v98
	v_cvt_pk_bf16_f32 v0, v0, v1
	global_store_short v[100:101], v0, off
.LBB0_427:
	s_or_b64 exec, exec, s[16:17]
	v_lshlrev_b32_e32 v100, 16, v174
	v_and_b32_e32 v101, 0xffff0000, v174
	v_lshlrev_b32_e32 v102, 16, v175
	v_and_b32_e32 v103, 0xffff0000, v175
	v_lshlrev_b32_e32 v104, 16, v176
	v_and_b32_e32 v105, 0xffff0000, v176
	v_lshlrev_b32_e32 v106, 16, v177
	v_and_b32_e32 v107, 0xffff0000, v177
	v_pk_add_f32 v[96:97], v[96:97], v[102:103]
	v_pk_add_f32 v[94:95], v[94:95], v[100:101]
	v_pk_add_f32 v[100:101], v[92:93], v[106:107]
	v_pk_add_f32 v[92:93], v[90:91], v[104:105]
	v_mul_f32_e32 v0, v95, v95
	v_mul_f32_e32 v90, v97, v97
	v_fmac_f32_e32 v0, v94, v94
	v_fmac_f32_e32 v90, v96, v96
	v_add_f32_e32 v0, v0, v90
	v_mul_f32_e32 v90, v93, v93
	v_mul_f32_e32 v91, v101, v101
	v_fmac_f32_e32 v90, v92, v92
	v_fmac_f32_e32 v91, v100, v100
	v_lshlrev_b64 v[98:99], 11, v[228:229]
	v_add_f32_e32 v90, v90, v91
	v_add_f32_e32 v0, v0, v90
	v_cvt_pk_bf16_f32 v90, v94, v95
	v_lshl_add_u64 v[94:95], v[98:99], 1, v[202:203]
	v_cvt_pk_bf16_f32 v91, v96, v97
	v_cvt_pk_bf16_f32 v92, v92, v93
	v_cvt_pk_bf16_f32 v93, v100, v101
	v_lshl_add_u64 v[94:95], v[216:217], 1, v[94:95]
	ds_bpermute_b32 v244, v255, v90
	ds_bpermute_b32 v245, v255, v91
	ds_bpermute_b32 v246, v255, v92
	ds_bpermute_b32 v247, v255, v93
	v_lshlrev_b32_e32 v96, 16, v172
	v_and_b32_e32 v97, 0xffff0000, v172
	v_lshlrev_b32_e32 v90, 16, v170
	v_and_b32_e32 v91, 0xffff0000, v170
	v_lshlrev_b32_e32 v92, 16, v171
	v_and_b32_e32 v93, 0xffff0000, v171
	v_lshlrev_b32_e32 v98, 16, v173
	v_and_b32_e32 v99, 0xffff0000, v173
	v_pk_add_f32 v[88:89], v[88:89], v[92:93]
	v_pk_add_f32 v[86:87], v[86:87], v[90:91]
	v_pk_add_f32 v[90:91], v[84:85], v[98:99]
	v_pk_add_f32 v[84:85], v[82:83], v[96:97]
	v_mul_f32_e32 v82, v87, v87
	v_mul_f32_e32 v83, v89, v89
	v_fmac_f32_e32 v82, v86, v86
	v_fmac_f32_e32 v83, v88, v88
	v_add_f32_e32 v82, v82, v83
	v_mul_f32_e32 v83, v85, v85
	v_mul_f32_e32 v92, v91, v91
	v_fmac_f32_e32 v83, v84, v84
	v_fmac_f32_e32 v92, v90, v90
	v_add_f32_e32 v83, v83, v92
	v_add_f32_e32 v82, v82, v83
	v_add_f32_e32 v0, v0, v82
	v_cvt_pk_bf16_f32 v82, v86, v87
	v_cvt_pk_bf16_f32 v83, v88, v89
	v_cvt_pk_bf16_f32 v84, v84, v85
	v_cvt_pk_bf16_f32 v85, v90, v91
	ds_bpermute_b32 v82, v255, v82
	ds_bpermute_b32 v83, v255, v83
	ds_bpermute_b32 v84, v255, v84
	ds_bpermute_b32 v85, v255, v85
	v_lshl_add_u64 v[94:95], v[94:95], 0, v[248:249]
	s_waitcnt lgkmcnt(4)
	global_store_dwordx4 v[94:95], v[244:247], off
	s_waitcnt lgkmcnt(0)
	global_store_dwordx4 v[94:95], v[82:85], off offset:256
	s_nop 1
	v_mov_b32_e32 v82, v0
	s_nop 1
	v_permlane16_swap_b32_e32 v0, v82
	v_add_f32_e32 v0, v0, v82
	v_mov_b32_e32 v82, v0
	s_nop 1
	v_permlane32_swap_b32_e32 v0, v82
	s_and_saveexec_b64 s[16:17], s[6:7]
	s_cbranch_execz .LBB0_429
	v_lshlrev_b64 v[84:85], 6, v[228:229]
	v_lshl_add_u64 v[84:85], v[204:205], 0, v[84:85]
	v_lshl_add_u64 v[84:85], s[14:15], 1, v[84:85]
	s_lshl_b32 s18, s29, 1
	s_mov_b32 s19, s40
	v_lshl_add_u64 v[84:85], v[84:85], 0, s[18:19]
	v_add_f32_e32 v0, v0, v82
	v_cvt_pk_bf16_f32 v0, v0, v1
	global_store_short v[84:85], v0, off
.LBB0_429:
	s_or_b64 exec, exec, s[16:17]
	v_lshlrev_b32_e32 v84, 16, v166
	v_and_b32_e32 v85, 0xffff0000, v166
	v_lshlrev_b32_e32 v86, 16, v167
	v_and_b32_e32 v87, 0xffff0000, v167
	v_lshlrev_b32_e32 v88, 16, v168
	v_and_b32_e32 v89, 0xffff0000, v168
	v_lshlrev_b32_e32 v90, 16, v169
	v_and_b32_e32 v91, 0xffff0000, v169
	v_pk_add_f32 v[80:81], v[80:81], v[86:87]
	v_pk_add_f32 v[78:79], v[78:79], v[84:85]
	v_pk_add_f32 v[84:85], v[76:77], v[90:91]
	v_pk_add_f32 v[76:77], v[74:75], v[88:89]
	v_mul_f32_e32 v0, v79, v79
	v_mul_f32_e32 v74, v81, v81
	v_fmac_f32_e32 v0, v78, v78
	v_fmac_f32_e32 v74, v80, v80
	v_add_f32_e32 v0, v0, v74
	v_mul_f32_e32 v74, v77, v77
	v_mul_f32_e32 v75, v85, v85
	v_fmac_f32_e32 v74, v76, v76
	v_fmac_f32_e32 v75, v84, v84
	v_lshlrev_b64 v[82:83], 11, v[226:227]
	v_add_f32_e32 v74, v74, v75
	v_add_f32_e32 v0, v0, v74
	v_cvt_pk_bf16_f32 v74, v78, v79
	v_lshl_add_u64 v[78:79], v[82:83], 1, v[202:203]
	v_cvt_pk_bf16_f32 v75, v80, v81
	v_cvt_pk_bf16_f32 v76, v76, v77
	v_cvt_pk_bf16_f32 v77, v84, v85
	v_lshl_add_u64 v[78:79], v[216:217], 1, v[78:79]
	ds_bpermute_b32 v244, v255, v74
	ds_bpermute_b32 v245, v255, v75
	ds_bpermute_b32 v246, v255, v76
	ds_bpermute_b32 v247, v255, v77
	v_lshlrev_b32_e32 v80, 16, v164
	v_and_b32_e32 v81, 0xffff0000, v164
	v_lshlrev_b32_e32 v74, 16, v162
	v_and_b32_e32 v75, 0xffff0000, v162
	v_lshlrev_b32_e32 v76, 16, v163
	v_and_b32_e32 v77, 0xffff0000, v163
	v_lshlrev_b32_e32 v82, 16, v165
	v_and_b32_e32 v83, 0xffff0000, v165
	v_pk_add_f32 v[72:73], v[72:73], v[76:77]
	v_pk_add_f32 v[70:71], v[70:71], v[74:75]
	v_pk_add_f32 v[74:75], v[68:69], v[82:83]
	v_pk_add_f32 v[68:69], v[66:67], v[80:81]
	v_mul_f32_e32 v66, v71, v71
	v_mul_f32_e32 v67, v73, v73
	v_fmac_f32_e32 v66, v70, v70
	v_fmac_f32_e32 v67, v72, v72
	v_add_f32_e32 v66, v66, v67
	v_mul_f32_e32 v67, v69, v69
	v_mul_f32_e32 v76, v75, v75
	v_fmac_f32_e32 v67, v68, v68
	v_fmac_f32_e32 v76, v74, v74
	v_add_f32_e32 v67, v67, v76
	v_add_f32_e32 v66, v66, v67
	v_add_f32_e32 v0, v0, v66
	v_cvt_pk_bf16_f32 v66, v70, v71
	v_cvt_pk_bf16_f32 v67, v72, v73
	v_cvt_pk_bf16_f32 v68, v68, v69
	v_cvt_pk_bf16_f32 v69, v74, v75
	ds_bpermute_b32 v66, v255, v66
	ds_bpermute_b32 v67, v255, v67
	ds_bpermute_b32 v68, v255, v68
	ds_bpermute_b32 v69, v255, v69
	v_lshl_add_u64 v[78:79], v[78:79], 0, v[248:249]
	s_waitcnt lgkmcnt(4)
	global_store_dwordx4 v[78:79], v[244:247], off
	s_waitcnt lgkmcnt(0)
	global_store_dwordx4 v[78:79], v[66:69], off offset:256
	s_nop 1
	v_mov_b32_e32 v66, v0
	s_nop 1
	v_permlane16_swap_b32_e32 v0, v66
	v_add_f32_e32 v0, v0, v66
	v_mov_b32_e32 v66, v0
	s_nop 1
	v_permlane32_swap_b32_e32 v0, v66
	s_and_saveexec_b64 s[16:17], s[6:7]
	s_cbranch_execz .LBB0_431
	v_lshlrev_b64 v[68:69], 6, v[226:227]
	v_lshl_add_u64 v[68:69], v[204:205], 0, v[68:69]
	v_lshl_add_u64 v[68:69], s[14:15], 1, v[68:69]
	s_lshl_b32 s18, s29, 1
	s_mov_b32 s19, s40
	v_lshl_add_u64 v[68:69], v[68:69], 0, s[18:19]
	v_add_f32_e32 v0, v0, v66
	v_cvt_pk_bf16_f32 v0, v0, v1
	global_store_short v[68:69], v0, off
.LBB0_431:
	s_or_b64 exec, exec, s[16:17]
	v_lshlrev_b32_e32 v68, 16, v158
	v_and_b32_e32 v69, 0xffff0000, v158
	v_lshlrev_b32_e32 v70, 16, v159
	v_and_b32_e32 v71, 0xffff0000, v159
	v_lshlrev_b32_e32 v72, 16, v160
	v_and_b32_e32 v73, 0xffff0000, v160
	v_lshlrev_b32_e32 v74, 16, v161
	v_and_b32_e32 v75, 0xffff0000, v161
	v_pk_add_f32 v[64:65], v[64:65], v[70:71]
	v_pk_add_f32 v[62:63], v[62:63], v[68:69]
	v_pk_add_f32 v[68:69], v[60:61], v[74:75]
	v_pk_add_f32 v[60:61], v[58:59], v[72:73]
	v_mul_f32_e32 v0, v63, v63
	v_mul_f32_e32 v58, v65, v65
	v_fmac_f32_e32 v0, v62, v62
	v_fmac_f32_e32 v58, v64, v64
	v_add_f32_e32 v0, v0, v58
	v_mul_f32_e32 v58, v61, v61
	v_mul_f32_e32 v59, v69, v69
	v_fmac_f32_e32 v58, v60, v60
	v_fmac_f32_e32 v59, v68, v68
	v_lshlrev_b64 v[66:67], 11, v[224:225]
	v_add_f32_e32 v58, v58, v59
	v_add_f32_e32 v0, v0, v58
	v_cvt_pk_bf16_f32 v58, v62, v63
	v_lshl_add_u64 v[62:63], v[66:67], 1, v[202:203]
	v_cvt_pk_bf16_f32 v59, v64, v65
	v_cvt_pk_bf16_f32 v60, v60, v61
	v_cvt_pk_bf16_f32 v61, v68, v69
	v_lshl_add_u64 v[62:63], v[216:217], 1, v[62:63]
	ds_bpermute_b32 v244, v255, v58
	ds_bpermute_b32 v245, v255, v59
	ds_bpermute_b32 v246, v255, v60
	ds_bpermute_b32 v247, v255, v61
	v_lshlrev_b32_e32 v64, 16, v156
	v_and_b32_e32 v65, 0xffff0000, v156
	v_lshlrev_b32_e32 v58, 16, v154
	v_and_b32_e32 v59, 0xffff0000, v154
	v_lshlrev_b32_e32 v60, 16, v155
	v_and_b32_e32 v61, 0xffff0000, v155
	v_lshlrev_b32_e32 v66, 16, v157
	v_and_b32_e32 v67, 0xffff0000, v157
	v_pk_add_f32 v[56:57], v[56:57], v[60:61]
	v_pk_add_f32 v[54:55], v[54:55], v[58:59]
	v_pk_add_f32 v[58:59], v[52:53], v[66:67]
	v_pk_add_f32 v[52:53], v[50:51], v[64:65]
	v_mul_f32_e32 v50, v55, v55
	v_mul_f32_e32 v51, v57, v57
	v_fmac_f32_e32 v50, v54, v54
	v_fmac_f32_e32 v51, v56, v56
	v_add_f32_e32 v50, v50, v51
	v_mul_f32_e32 v51, v53, v53
	v_mul_f32_e32 v60, v59, v59
	v_fmac_f32_e32 v51, v52, v52
	v_fmac_f32_e32 v60, v58, v58
	v_add_f32_e32 v51, v51, v60
	v_add_f32_e32 v50, v50, v51
	v_add_f32_e32 v0, v0, v50
	v_cvt_pk_bf16_f32 v50, v54, v55
	v_cvt_pk_bf16_f32 v51, v56, v57
	v_cvt_pk_bf16_f32 v52, v52, v53
	v_cvt_pk_bf16_f32 v53, v58, v59
	ds_bpermute_b32 v50, v255, v50
	ds_bpermute_b32 v51, v255, v51
	ds_bpermute_b32 v52, v255, v52
	ds_bpermute_b32 v53, v255, v53
	v_lshl_add_u64 v[62:63], v[62:63], 0, v[248:249]
	s_waitcnt lgkmcnt(4)
	global_store_dwordx4 v[62:63], v[244:247], off
	s_waitcnt lgkmcnt(0)
	global_store_dwordx4 v[62:63], v[50:53], off offset:256
	s_nop 1
	v_mov_b32_e32 v50, v0
	s_nop 1
	v_permlane16_swap_b32_e32 v0, v50
	v_add_f32_e32 v0, v0, v50
	v_mov_b32_e32 v50, v0
	s_nop 1
	v_permlane32_swap_b32_e32 v0, v50
	s_and_saveexec_b64 s[16:17], s[6:7]
	s_cbranch_execz .LBB0_433
	v_lshlrev_b64 v[52:53], 6, v[224:225]
	v_lshl_add_u64 v[52:53], v[204:205], 0, v[52:53]
	v_lshl_add_u64 v[52:53], s[14:15], 1, v[52:53]
	s_lshl_b32 s18, s29, 1
	s_mov_b32 s19, s40
	v_lshl_add_u64 v[52:53], v[52:53], 0, s[18:19]
	v_add_f32_e32 v0, v0, v50
	v_cvt_pk_bf16_f32 v0, v0, v1
	global_store_short v[52:53], v0, off
.LBB0_433:
	s_or_b64 exec, exec, s[16:17]
	v_lshlrev_b32_e32 v52, 16, v150
	v_and_b32_e32 v53, 0xffff0000, v150
	v_lshlrev_b32_e32 v54, 16, v151
	v_and_b32_e32 v55, 0xffff0000, v151
	v_lshlrev_b32_e32 v56, 16, v152
	v_and_b32_e32 v57, 0xffff0000, v152
	v_lshlrev_b32_e32 v58, 16, v153
	v_and_b32_e32 v59, 0xffff0000, v153
	v_pk_add_f32 v[48:49], v[48:49], v[54:55]
	v_pk_add_f32 v[46:47], v[46:47], v[52:53]
	v_pk_add_f32 v[52:53], v[44:45], v[58:59]
	v_pk_add_f32 v[44:45], v[42:43], v[56:57]
	v_mul_f32_e32 v0, v47, v47
	v_mul_f32_e32 v42, v49, v49
	v_fmac_f32_e32 v0, v46, v46
	v_fmac_f32_e32 v42, v48, v48
	v_add_f32_e32 v0, v0, v42
	v_mul_f32_e32 v42, v45, v45
	v_mul_f32_e32 v43, v53, v53
	v_fmac_f32_e32 v42, v44, v44
	v_fmac_f32_e32 v43, v52, v52
	v_lshlrev_b64 v[50:51], 11, v[222:223]
	v_add_f32_e32 v42, v42, v43
	v_add_f32_e32 v0, v0, v42
	v_cvt_pk_bf16_f32 v42, v46, v47
	v_lshl_add_u64 v[46:47], v[50:51], 1, v[202:203]
	v_cvt_pk_bf16_f32 v43, v48, v49
	v_cvt_pk_bf16_f32 v44, v44, v45
	v_cvt_pk_bf16_f32 v45, v52, v53
	v_lshl_add_u64 v[46:47], v[216:217], 1, v[46:47]
	ds_bpermute_b32 v244, v255, v42
	ds_bpermute_b32 v245, v255, v43
	ds_bpermute_b32 v246, v255, v44
	ds_bpermute_b32 v247, v255, v45
	v_lshlrev_b32_e32 v48, 16, v148
	v_and_b32_e32 v49, 0xffff0000, v148
	v_lshlrev_b32_e32 v42, 16, v146
	v_and_b32_e32 v43, 0xffff0000, v146
	v_lshlrev_b32_e32 v44, 16, v147
	v_and_b32_e32 v45, 0xffff0000, v147
	v_lshlrev_b32_e32 v50, 16, v149
	v_and_b32_e32 v51, 0xffff0000, v149
	v_pk_add_f32 v[40:41], v[40:41], v[44:45]
	v_pk_add_f32 v[38:39], v[38:39], v[42:43]
	v_pk_add_f32 v[42:43], v[36:37], v[50:51]
	v_pk_add_f32 v[36:37], v[34:35], v[48:49]
	v_mul_f32_e32 v34, v39, v39
	v_mul_f32_e32 v35, v41, v41
	v_fmac_f32_e32 v34, v38, v38
	v_fmac_f32_e32 v35, v40, v40
	v_add_f32_e32 v34, v34, v35
	v_mul_f32_e32 v35, v37, v37
	v_mul_f32_e32 v44, v43, v43
	v_fmac_f32_e32 v35, v36, v36
	v_fmac_f32_e32 v44, v42, v42
	v_add_f32_e32 v35, v35, v44
	v_add_f32_e32 v34, v34, v35
	v_add_f32_e32 v0, v0, v34
	v_cvt_pk_bf16_f32 v34, v38, v39
	v_cvt_pk_bf16_f32 v35, v40, v41
	v_cvt_pk_bf16_f32 v36, v36, v37
	v_cvt_pk_bf16_f32 v37, v42, v43
	ds_bpermute_b32 v34, v255, v34
	ds_bpermute_b32 v35, v255, v35
	ds_bpermute_b32 v36, v255, v36
	ds_bpermute_b32 v37, v255, v37
	v_lshl_add_u64 v[46:47], v[46:47], 0, v[248:249]
	s_waitcnt lgkmcnt(4)
	global_store_dwordx4 v[46:47], v[244:247], off
	s_waitcnt lgkmcnt(0)
	global_store_dwordx4 v[46:47], v[34:37], off offset:256
	s_nop 1
	v_mov_b32_e32 v34, v0
	s_nop 1
	v_permlane16_swap_b32_e32 v0, v34
	v_add_f32_e32 v0, v0, v34
	v_mov_b32_e32 v34, v0
	s_nop 1
	v_permlane32_swap_b32_e32 v0, v34
	s_and_saveexec_b64 s[16:17], s[6:7]
	s_cbranch_execz .LBB0_435
	v_lshlrev_b64 v[36:37], 6, v[222:223]
	v_lshl_add_u64 v[36:37], v[204:205], 0, v[36:37]
	v_lshl_add_u64 v[36:37], s[14:15], 1, v[36:37]
	s_lshl_b32 s18, s29, 1
	s_mov_b32 s19, s40
	v_lshl_add_u64 v[36:37], v[36:37], 0, s[18:19]
	v_add_f32_e32 v0, v0, v34
	v_cvt_pk_bf16_f32 v0, v0, v1
	global_store_short v[36:37], v0, off
.LBB0_435:
	s_or_b64 exec, exec, s[16:17]
	v_lshlrev_b32_e32 v36, 16, v138
	v_and_b32_e32 v37, 0xffff0000, v138
	v_lshlrev_b32_e32 v38, 16, v139
	v_and_b32_e32 v39, 0xffff0000, v139
	v_lshlrev_b32_e32 v40, 16, v140
	v_and_b32_e32 v41, 0xffff0000, v140
	v_lshlrev_b32_e32 v42, 16, v141
	v_and_b32_e32 v43, 0xffff0000, v141
	v_pk_add_f32 v[32:33], v[32:33], v[38:39]
	v_pk_add_f32 v[30:31], v[30:31], v[36:37]
	v_pk_add_f32 v[36:37], v[28:29], v[42:43]
	v_pk_add_f32 v[28:29], v[26:27], v[40:41]
	v_mul_f32_e32 v0, v31, v31
	v_mul_f32_e32 v26, v33, v33
	v_fmac_f32_e32 v0, v30, v30
	v_fmac_f32_e32 v26, v32, v32
	v_add_f32_e32 v0, v0, v26
	v_mul_f32_e32 v26, v29, v29
	v_mul_f32_e32 v27, v37, v37
	v_fmac_f32_e32 v26, v28, v28
	v_fmac_f32_e32 v27, v36, v36
	v_lshlrev_b64 v[34:35], 11, v[220:221]
	v_add_f32_e32 v26, v26, v27
	v_add_f32_e32 v0, v0, v26
	v_cvt_pk_bf16_f32 v26, v30, v31
	v_lshl_add_u64 v[30:31], v[34:35], 1, v[202:203]
	v_cvt_pk_bf16_f32 v27, v32, v33
	v_cvt_pk_bf16_f32 v28, v28, v29
	v_cvt_pk_bf16_f32 v29, v36, v37
	v_lshl_add_u64 v[30:31], v[216:217], 1, v[30:31]
	ds_bpermute_b32 v244, v255, v26
	ds_bpermute_b32 v245, v255, v27
	ds_bpermute_b32 v246, v255, v28
	ds_bpermute_b32 v247, v255, v29
	v_lshlrev_b32_e32 v32, 16, v132
	v_and_b32_e32 v33, 0xffff0000, v132
	v_lshlrev_b32_e32 v26, 16, v130
	v_and_b32_e32 v27, 0xffff0000, v130
	v_lshlrev_b32_e32 v28, 16, v131
	v_and_b32_e32 v29, 0xffff0000, v131
	v_lshlrev_b32_e32 v34, 16, v133
	v_and_b32_e32 v35, 0xffff0000, v133
	v_pk_add_f32 v[24:25], v[24:25], v[28:29]
	v_pk_add_f32 v[22:23], v[22:23], v[26:27]
	v_pk_add_f32 v[26:27], v[20:21], v[34:35]
	v_pk_add_f32 v[20:21], v[18:19], v[32:33]
	v_mul_f32_e32 v18, v23, v23
	v_mul_f32_e32 v19, v25, v25
	v_fmac_f32_e32 v18, v22, v22
	v_fmac_f32_e32 v19, v24, v24
	v_add_f32_e32 v18, v18, v19
	v_mul_f32_e32 v19, v21, v21
	v_mul_f32_e32 v28, v27, v27
	v_fmac_f32_e32 v19, v20, v20
	v_fmac_f32_e32 v28, v26, v26
	v_add_f32_e32 v19, v19, v28
	v_add_f32_e32 v18, v18, v19
	v_add_f32_e32 v0, v0, v18
	v_cvt_pk_bf16_f32 v18, v22, v23
	v_cvt_pk_bf16_f32 v19, v24, v25
	v_cvt_pk_bf16_f32 v20, v20, v21
	v_cvt_pk_bf16_f32 v21, v26, v27
	ds_bpermute_b32 v18, v255, v18
	ds_bpermute_b32 v19, v255, v19
	ds_bpermute_b32 v20, v255, v20
	ds_bpermute_b32 v21, v255, v21
	v_lshl_add_u64 v[30:31], v[30:31], 0, v[248:249]
	s_waitcnt lgkmcnt(4)
	global_store_dwordx4 v[30:31], v[244:247], off
	s_waitcnt lgkmcnt(0)
	global_store_dwordx4 v[30:31], v[18:21], off offset:256
	s_nop 1
	v_mov_b32_e32 v18, v0
	s_nop 1
	v_permlane16_swap_b32_e32 v0, v18
	v_add_f32_e32 v0, v0, v18
	v_mov_b32_e32 v18, v0
	s_nop 1
	v_permlane32_swap_b32_e32 v0, v18
	s_and_saveexec_b64 s[16:17], s[6:7]
	s_cbranch_execz .LBB0_437
	v_lshlrev_b64 v[20:21], 6, v[220:221]
	v_lshl_add_u64 v[20:21], v[204:205], 0, v[20:21]
	v_lshl_add_u64 v[20:21], s[14:15], 1, v[20:21]
	s_lshl_b32 s18, s29, 1
	s_mov_b32 s19, s40
	v_lshl_add_u64 v[20:21], v[20:21], 0, s[18:19]
	v_add_f32_e32 v0, v0, v18
	v_cvt_pk_bf16_f32 v0, v0, v1
	global_store_short v[20:21], v0, off
.LBB0_437:
	s_or_b64 exec, exec, s[16:17]
	v_lshlrev_b32_e32 v20, 16, v142
	v_and_b32_e32 v21, 0xffff0000, v142
	v_lshlrev_b32_e32 v22, 16, v143
	v_and_b32_e32 v23, 0xffff0000, v143
	v_lshlrev_b32_e32 v24, 16, v144
	v_and_b32_e32 v25, 0xffff0000, v144
	v_lshlrev_b32_e32 v26, 16, v145
	v_and_b32_e32 v27, 0xffff0000, v145
	v_pk_add_f32 v[16:17], v[16:17], v[22:23]
	v_pk_add_f32 v[14:15], v[14:15], v[20:21]
	v_pk_add_f32 v[20:21], v[12:13], v[26:27]
	v_pk_add_f32 v[12:13], v[10:11], v[24:25]
	v_mul_f32_e32 v0, v15, v15
	v_mul_f32_e32 v10, v17, v17
	v_fmac_f32_e32 v0, v14, v14
	v_fmac_f32_e32 v10, v16, v16
	v_add_f32_e32 v0, v0, v10
	v_mul_f32_e32 v10, v13, v13
	v_mul_f32_e32 v11, v21, v21
	v_fmac_f32_e32 v10, v12, v12
	v_fmac_f32_e32 v11, v20, v20
	v_lshlrev_b64 v[18:19], 11, v[218:219]
	v_add_f32_e32 v10, v10, v11
	v_add_f32_e32 v0, v0, v10
	v_cvt_pk_bf16_f32 v10, v14, v15
	v_lshl_add_u64 v[14:15], v[18:19], 1, v[202:203]
	v_cvt_pk_bf16_f32 v11, v16, v17
	v_cvt_pk_bf16_f32 v12, v12, v13
	v_cvt_pk_bf16_f32 v13, v20, v21
	v_lshl_add_u64 v[14:15], v[216:217], 1, v[14:15]
	ds_bpermute_b32 v244, v255, v10
	ds_bpermute_b32 v245, v255, v11
	ds_bpermute_b32 v246, v255, v12
	ds_bpermute_b32 v247, v255, v13
	v_lshlrev_b32_e32 v16, 16, v136
	v_and_b32_e32 v17, 0xffff0000, v136
	v_lshlrev_b32_e32 v10, 16, v134
	v_and_b32_e32 v11, 0xffff0000, v134
	v_lshlrev_b32_e32 v12, 16, v135
	v_and_b32_e32 v13, 0xffff0000, v135
	v_lshlrev_b32_e32 v18, 16, v137
	v_and_b32_e32 v19, 0xffff0000, v137
	v_pk_add_f32 v[8:9], v[8:9], v[12:13]
	v_pk_add_f32 v[6:7], v[6:7], v[10:11]
	v_pk_add_f32 v[10:11], v[4:5], v[18:19]
	v_pk_add_f32 v[4:5], v[2:3], v[16:17]
	v_mul_f32_e32 v2, v7, v7
	v_mul_f32_e32 v3, v9, v9
	v_fmac_f32_e32 v2, v6, v6
	v_fmac_f32_e32 v3, v8, v8
	v_add_f32_e32 v2, v2, v3
	v_mul_f32_e32 v3, v5, v5
	v_mul_f32_e32 v12, v11, v11
	v_fmac_f32_e32 v3, v4, v4
	v_fmac_f32_e32 v12, v10, v10
	v_add_f32_e32 v3, v3, v12
	v_add_f32_e32 v2, v2, v3
	v_add_f32_e32 v0, v0, v2
	v_cvt_pk_bf16_f32 v2, v6, v7
	v_cvt_pk_bf16_f32 v3, v8, v9
	v_cvt_pk_bf16_f32 v4, v4, v5
	v_cvt_pk_bf16_f32 v5, v10, v11
	ds_bpermute_b32 v2, v255, v2
	ds_bpermute_b32 v3, v255, v3
	ds_bpermute_b32 v4, v255, v4
	ds_bpermute_b32 v5, v255, v5
	v_lshl_add_u64 v[14:15], v[14:15], 0, v[248:249]
	s_waitcnt lgkmcnt(4)
	global_store_dwordx4 v[14:15], v[244:247], off
	s_waitcnt lgkmcnt(0)
	global_store_dwordx4 v[14:15], v[2:5], off offset:256
	s_nop 1
	v_mov_b32_e32 v2, v0
	s_nop 1
	v_permlane16_swap_b32_e32 v0, v2
	v_add_f32_e32 v0, v0, v2
	v_mov_b32_e32 v2, v0
	s_nop 1
	v_permlane32_swap_b32_e32 v0, v2
	s_and_saveexec_b64 s[16:17], s[6:7]
	s_cbranch_execz .LBB0_439
	v_lshlrev_b64 v[4:5], 6, v[218:219]
	v_lshl_add_u64 v[4:5], v[204:205], 0, v[4:5]
	v_lshl_add_u64 v[4:5], s[14:15], 1, v[4:5]
	s_lshl_b32 s14, s29, 1
	s_mov_b32 s15, s40
	v_lshl_add_u64 v[4:5], v[4:5], 0, s[14:15]
	v_add_f32_e32 v0, v0, v2
	v_cvt_pk_bf16_f32 v0, v0, v1
	global_store_short v[4:5], v0, off

.LBB0_1086:
	v_mbcnt_lo_u32_b32 v255, -1, 0
	v_mbcnt_hi_u32_b32 v255, -1, v255
	v_lshrrev_b32_e32 v244, 2, v255
	v_and_b32_e32 v245, 3, v255
	v_and_b32_e32 v246, 15, v255
	v_lshrrev_b32_e32 v247, 4, v255
	v_sub_u32_e32 v246, v244, v246
	v_sub_u32_e32 v247, v245, v247
	v_mul_i32_i24_e32 v246, 0x1000, v246
	v_lshl_add_u32 v248, v247, 4, v246
	v_ashrrev_i32_e32 v249, 31, v248
	v_lshl_add_u32 v255, v245, 4, v244
	v_lshlrev_b32_e32 v255, 2, v255
	v_lshl_or_b32 v216, s12, 8, v250
	v_lshl_add_u32 v232, s28, 8, v238
	v_ashrrev_i32_e32 v217, 31, v216
	v_lshlrev_b64 v[234:235], 1, v[216:217]
	v_ashrrev_i32_e32 v233, 31, v232
	v_lshl_add_u64 v[134:135], v[202:203], 0, v[234:235]
	v_lshlrev_b64 v[236:237], 12, v[232:233]
	v_lshl_add_u64 v[130:131], v[134:135], 0, v[236:237]
	global_load_dwordx4 v[190:193], v[130:131], off
	global_load_dwordx4 v[186:189], v[130:131], off offset:256
	v_or_b32_e32 v230, 16, v232
	v_ashrrev_i32_e32 v231, 31, v230
	v_lshlrev_b64 v[130:131], 12, v[230:231]
	v_or_b32_e32 v228, 32, v232
	v_lshl_add_u64 v[130:131], v[134:135], 0, v[130:131]
	v_ashrrev_i32_e32 v229, 31, v228
	global_load_dwordx4 v[182:185], v[130:131], off
	global_load_dwordx4 v[178:181], v[130:131], off offset:256
	v_lshlrev_b64 v[130:131], 12, v[228:229]
	v_or_b32_e32 v226, 48, v232
	v_lshl_add_u64 v[130:131], v[134:135], 0, v[130:131]
	v_ashrrev_i32_e32 v227, 31, v226
	global_load_dwordx4 v[174:177], v[130:131], off
	global_load_dwordx4 v[170:173], v[130:131], off offset:256
	v_lshlrev_b64 v[130:131], 12, v[226:227]
	v_add_u32_e32 v224, 0x80, v232
	v_lshl_add_u64 v[130:131], v[134:135], 0, v[130:131]
	v_ashrrev_i32_e32 v225, 31, v224
	global_load_dwordx4 v[166:169], v[130:131], off
	global_load_dwordx4 v[162:165], v[130:131], off offset:256
	v_lshlrev_b64 v[130:131], 12, v[224:225]
	v_add_u32_e32 v222, 0x90, v232
	v_lshl_add_u64 v[130:131], v[134:135], 0, v[130:131]
	v_ashrrev_i32_e32 v223, 31, v222
	global_load_dwordx4 v[158:161], v[130:131], off
	global_load_dwordx4 v[154:157], v[130:131], off offset:256
	v_lshlrev_b64 v[130:131], 12, v[222:223]
	v_add_u32_e32 v220, 0xa0, v232
	v_add_u32_e32 v218, 0xb0, v232
	v_lshl_add_u64 v[130:131], v[134:135], 0, v[130:131]
	v_ashrrev_i32_e32 v221, 31, v220
	v_ashrrev_i32_e32 v219, 31, v218
	global_load_dwordx4 v[150:153], v[130:131], off
	global_load_dwordx4 v[146:149], v[130:131], off offset:256
	v_lshlrev_b64 v[130:131], 12, v[220:221]
	v_lshlrev_b64 v[136:137], 12, v[218:219]
	v_lshl_add_u64 v[130:131], v[134:135], 0, v[130:131]
	v_lshl_add_u64 v[134:135], v[134:135], 0, v[136:137]
	global_load_dwordx4 v[138:141], v[130:131], off
	s_nop 0
	global_load_dwordx4 v[130:133], v[130:131], off offset:256
	s_nop 0
	global_load_dwordx4 v[142:145], v[134:135], off
	s_nop 0
	global_load_dwordx4 v[134:137], v[134:135], off offset:256
	s_mov_b64 vcc, s[2:3]
	s_cbranch_vccz .Lalign_skip_4
	s_barrier
.Lalign_skip_4:
	s_lshl_b32 s8, s12, 2
	s_ashr_i32 s9, s8, 31
	s_waitcnt vmcnt(0)
	v_lshlrev_b32_e32 v252, 16, v190
	v_and_b32_e32 v253, 0xffff0000, v190
	v_lshlrev_b32_e32 v190, 16, v191
	v_and_b32_e32 v191, 0xffff0000, v191
	v_pk_add_f32 v[124:125], v[124:125], v[190:191]
	v_pk_add_f32 v[122:123], v[122:123], v[252:253]
	v_lshlrev_b32_e32 v206, 16, v192
	v_and_b32_e32 v207, 0xffff0000, v192
	v_mul_f32_e32 v0, v123, v123
	v_mul_f32_e32 v190, v125, v125
	v_pk_add_f32 v[126:127], v[126:127], v[206:207]
	v_fmac_f32_e32 v0, v122, v122
	v_fmac_f32_e32 v190, v124, v124
	v_add_f32_e32 v0, v0, v190
	v_mul_f32_e32 v190, v127, v127
	v_lshlrev_b32_e32 v192, 16, v193
	v_and_b32_e32 v193, 0xffff0000, v193
	v_fmac_f32_e32 v190, v126, v126
	v_cvt_pk_bf16_f32 v122, v122, v123
	v_cvt_pk_bf16_f32 v123, v124, v125
	v_cvt_pk_bf16_f32 v124, v126, v127
	v_lshl_add_u64 v[126:127], v[202:203], 0, v[236:237]
	v_pk_add_f32 v[128:129], v[128:129], v[192:193]
	v_lshl_add_u64 v[126:127], v[126:127], 0, v[234:235]
	v_cvt_pk_bf16_f32 v125, v128, v129
	v_mul_f32_e32 v191, v129, v129
	ds_bpermute_b32 v244, v255, v122
	ds_bpermute_b32 v245, v255, v123
	ds_bpermute_b32 v246, v255, v124
	ds_bpermute_b32 v247, v255, v125
	v_fmac_f32_e32 v191, v128, v128
	v_lshlrev_b32_e32 v128, 16, v188
	v_lshlrev_b32_e32 v122, 16, v186
	v_and_b32_e32 v123, 0xffff0000, v186
	v_lshlrev_b32_e32 v124, 16, v187
	v_and_b32_e32 v125, 0xffff0000, v187
	v_and_b32_e32 v129, 0xffff0000, v188
	v_lshlrev_b32_e32 v186, 16, v189
	v_and_b32_e32 v187, 0xffff0000, v189
	v_pk_add_f32 v[120:121], v[120:121], v[124:125]
	v_pk_add_f32 v[118:119], v[118:119], v[122:123]
	v_pk_add_f32 v[122:123], v[116:117], v[186:187]
	v_pk_add_f32 v[116:117], v[114:115], v[128:129]
	v_mul_f32_e32 v114, v119, v119
	v_mul_f32_e32 v115, v121, v121
	v_fmac_f32_e32 v114, v118, v118
	v_fmac_f32_e32 v115, v120, v120
	v_add_f32_e32 v114, v114, v115
	v_mul_f32_e32 v115, v117, v117
	v_mul_f32_e32 v124, v123, v123
	v_fmac_f32_e32 v115, v116, v116
	v_fmac_f32_e32 v124, v122, v122
	v_add_f32_e32 v190, v190, v191
	v_add_f32_e32 v115, v115, v124
	v_add_f32_e32 v0, v0, v190
	v_add_f32_e32 v114, v114, v115
	v_add_f32_e32 v0, v0, v114
	v_cvt_pk_bf16_f32 v114, v118, v119
	v_cvt_pk_bf16_f32 v115, v120, v121
	v_cvt_pk_bf16_f32 v116, v116, v117
	v_cvt_pk_bf16_f32 v117, v122, v123
	ds_bpermute_b32 v114, v255, v114
	ds_bpermute_b32 v115, v255, v115
	ds_bpermute_b32 v116, v255, v116
	ds_bpermute_b32 v117, v255, v117
	v_lshl_add_u64 v[126:127], v[126:127], 0, v[248:249]
	s_waitcnt lgkmcnt(4)
	global_store_dwordx4 v[126:127], v[244:247], off
	s_waitcnt lgkmcnt(0)
	global_store_dwordx4 v[126:127], v[114:117], off offset:256
	s_nop 1
	v_mov_b32_e32 v114, v0
	s_nop 1
	v_permlane16_swap_b32_e32 v0, v114
	v_add_f32_e32 v0, v0, v114
	v_mov_b32_e32 v114, v0
	s_nop 1
	v_permlane32_swap_b32_e32 v0, v114
	s_and_saveexec_b64 s[12:13], s[4:5]
	s_cbranch_execz .LBB0_1088
	v_lshlrev_b64 v[116:117], 6, v[232:233]
	v_lshl_add_u64 v[116:117], v[204:205], 0, v[116:117]
	v_lshl_add_u64 v[116:117], s[8:9], 1, v[116:117]
	s_lshl_b32 s28, s23, 1
	s_mov_b32 s29, s40
	v_lshl_add_u64 v[116:117], v[116:117], 0, s[28:29]
	v_add_f32_e32 v0, v0, v114
	v_cvt_pk_bf16_f32 v0, v0, v1
	global_store_short v[116:117], v0, off
.LBB0_1088:
	s_or_b64 exec, exec, s[12:13]
	v_lshlrev_b32_e32 v116, 16, v182
	v_and_b32_e32 v117, 0xffff0000, v182
	v_lshlrev_b32_e32 v118, 16, v183
	v_and_b32_e32 v119, 0xffff0000, v183
	v_lshlrev_b32_e32 v120, 16, v184
	v_and_b32_e32 v121, 0xffff0000, v184
	v_lshlrev_b32_e32 v122, 16, v185
	v_and_b32_e32 v123, 0xffff0000, v185
	v_pk_add_f32 v[112:113], v[112:113], v[118:119]
	v_pk_add_f32 v[110:111], v[110:111], v[116:117]
	v_pk_add_f32 v[116:117], v[108:109], v[122:123]
	v_pk_add_f32 v[108:109], v[106:107], v[120:121]
	v_mul_f32_e32 v0, v111, v111
	v_mul_f32_e32 v106, v113, v113
	v_fmac_f32_e32 v0, v110, v110
	v_fmac_f32_e32 v106, v112, v112
	v_add_f32_e32 v0, v0, v106
	v_mul_f32_e32 v106, v109, v109
	v_mul_f32_e32 v107, v117, v117
	v_fmac_f32_e32 v106, v108, v108
	v_fmac_f32_e32 v107, v116, v116
	v_lshlrev_b64 v[114:115], 11, v[230:231]
	v_add_f32_e32 v106, v106, v107
	v_add_f32_e32 v0, v0, v106
	v_cvt_pk_bf16_f32 v106, v110, v111
	v_lshl_add_u64 v[110:111], v[114:115], 1, v[202:203]
	v_cvt_pk_bf16_f32 v107, v112, v113
	v_cvt_pk_bf16_f32 v108, v108, v109
	v_cvt_pk_bf16_f32 v109, v116, v117
	v_lshl_add_u64 v[110:111], v[216:217], 1, v[110:111]
	ds_bpermute_b32 v244, v255, v106
	ds_bpermute_b32 v245, v255, v107
	ds_bpermute_b32 v246, v255, v108
	ds_bpermute_b32 v247, v255, v109
	v_lshlrev_b32_e32 v112, 16, v180
	v_and_b32_e32 v113, 0xffff0000, v180
	v_lshlrev_b32_e32 v106, 16, v178
	v_and_b32_e32 v107, 0xffff0000, v178
	v_lshlrev_b32_e32 v108, 16, v179
	v_and_b32_e32 v109, 0xffff0000, v179
	v_lshlrev_b32_e32 v114, 16, v181
	v_and_b32_e32 v115, 0xffff0000, v181
	v_pk_add_f32 v[104:105], v[104:105], v[108:109]
	v_pk_add_f32 v[102:103], v[102:103], v[106:107]
	v_pk_add_f32 v[106:107], v[100:101], v[114:115]
	v_pk_add_f32 v[100:101], v[98:99], v[112:113]
	v_mul_f32_e32 v98, v103, v103
	v_mul_f32_e32 v99, v105, v105
	v_fmac_f32_e32 v98, v102, v102
	v_fmac_f32_e32 v99, v104, v104
	v_add_f32_e32 v98, v98, v99
	v_mul_f32_e32 v99, v101, v101
	v_mul_f32_e32 v108, v107, v107
	v_fmac_f32_e32 v99, v100, v100
	v_fmac_f32_e32 v108, v106, v106
	v_add_f32_e32 v99, v99, v108
	v_add_f32_e32 v98, v98, v99
	v_add_f32_e32 v0, v0, v98
	v_cvt_pk_bf16_f32 v98, v102, v103
	v_cvt_pk_bf16_f32 v99, v104, v105
	v_cvt_pk_bf16_f32 v100, v100, v101
	v_cvt_pk_bf16_f32 v101, v106, v107
	ds_bpermute_b32 v98, v255, v98
	ds_bpermute_b32 v99, v255, v99
	ds_bpermute_b32 v100, v255, v100
	ds_bpermute_b32 v101, v255, v101
	v_lshl_add_u64 v[110:111], v[110:111], 0, v[248:249]
	s_waitcnt lgkmcnt(4)
	global_store_dwordx4 v[110:111], v[244:247], off
	s_waitcnt lgkmcnt(0)
	global_store_dwordx4 v[110:111], v[98:101], off offset:256
	s_nop 1
	v_mov_b32_e32 v98, v0
	s_nop 1
	v_permlane16_swap_b32_e32 v0, v98
	v_add_f32_e32 v0, v0, v98
	v_mov_b32_e32 v98, v0
	s_nop 1
	v_permlane32_swap_b32_e32 v0, v98
	s_and_saveexec_b64 s[12:13], s[4:5]
	s_cbranch_execz .LBB0_1090
	v_lshlrev_b64 v[100:101], 6, v[230:231]
	v_lshl_add_u64 v[100:101], v[204:205], 0, v[100:101]
	v_lshl_add_u64 v[100:101], s[8:9], 1, v[100:101]
	s_lshl_b32 s28, s23, 1
	s_mov_b32 s29, s40
	v_lshl_add_u64 v[100:101], v[100:101], 0, s[28:29]
	v_add_f32_e32 v0, v0, v98
	v_cvt_pk_bf16_f32 v0, v0, v1
	global_store_short v[100:101], v0, off
.LBB0_1090:
	s_or_b64 exec, exec, s[12:13]
	v_lshlrev_b32_e32 v100, 16, v174
	v_and_b32_e32 v101, 0xffff0000, v174
	v_lshlrev_b32_e32 v102, 16, v175
	v_and_b32_e32 v103, 0xffff0000, v175
	v_lshlrev_b32_e32 v104, 16, v176
	v_and_b32_e32 v105, 0xffff0000, v176
	v_lshlrev_b32_e32 v106, 16, v177
	v_and_b32_e32 v107, 0xffff0000, v177
	v_pk_add_f32 v[96:97], v[96:97], v[102:103]
	v_pk_add_f32 v[94:95], v[94:95], v[100:101]
	v_pk_add_f32 v[100:101], v[92:93], v[106:107]
	v_pk_add_f32 v[92:93], v[90:91], v[104:105]
	v_mul_f32_e32 v0, v95, v95
	v_mul_f32_e32 v90, v97, v97
	v_fmac_f32_e32 v0, v94, v94
	v_fmac_f32_e32 v90, v96, v96
	v_add_f32_e32 v0, v0, v90
	v_mul_f32_e32 v90, v93, v93
	v_mul_f32_e32 v91, v101, v101
	v_fmac_f32_e32 v90, v92, v92
	v_fmac_f32_e32 v91, v100, v100
	v_lshlrev_b64 v[98:99], 11, v[228:229]
	v_add_f32_e32 v90, v90, v91
	v_add_f32_e32 v0, v0, v90
	v_cvt_pk_bf16_f32 v90, v94, v95
	v_lshl_add_u64 v[94:95], v[98:99], 1, v[202:203]
	v_cvt_pk_bf16_f32 v91, v96, v97
	v_cvt_pk_bf16_f32 v92, v92, v93
	v_cvt_pk_bf16_f32 v93, v100, v101
	v_lshl_add_u64 v[94:95], v[216:217], 1, v[94:95]
	ds_bpermute_b32 v244, v255, v90
	ds_bpermute_b32 v245, v255, v91
	ds_bpermute_b32 v246, v255, v92
	ds_bpermute_b32 v247, v255, v93
	v_lshlrev_b32_e32 v96, 16, v172
	v_and_b32_e32 v97, 0xffff0000, v172
	v_lshlrev_b32_e32 v90, 16, v170
	v_and_b32_e32 v91, 0xffff0000, v170
	v_lshlrev_b32_e32 v92, 16, v171
	v_and_b32_e32 v93, 0xffff0000, v171
	v_lshlrev_b32_e32 v98, 16, v173
	v_and_b32_e32 v99, 0xffff0000, v173
	v_pk_add_f32 v[88:89], v[88:89], v[92:93]
	v_pk_add_f32 v[86:87], v[86:87], v[90:91]
	v_pk_add_f32 v[90:91], v[84:85], v[98:99]
	v_pk_add_f32 v[84:85], v[82:83], v[96:97]
	v_mul_f32_e32 v82, v87, v87
	v_mul_f32_e32 v83, v89, v89
	v_fmac_f32_e32 v82, v86, v86
	v_fmac_f32_e32 v83, v88, v88
	v_add_f32_e32 v82, v82, v83
	v_mul_f32_e32 v83, v85, v85
	v_mul_f32_e32 v92, v91, v91
	v_fmac_f32_e32 v83, v84, v84
	v_fmac_f32_e32 v92, v90, v90
	v_add_f32_e32 v83, v83, v92
	v_add_f32_e32 v82, v82, v83
	v_add_f32_e32 v0, v0, v82
	v_cvt_pk_bf16_f32 v82, v86, v87
	v_cvt_pk_bf16_f32 v83, v88, v89
	v_cvt_pk_bf16_f32 v84, v84, v85
	v_cvt_pk_bf16_f32 v85, v90, v91
	ds_bpermute_b32 v82, v255, v82
	ds_bpermute_b32 v83, v255, v83
	ds_bpermute_b32 v84, v255, v84
	ds_bpermute_b32 v85, v255, v85
	v_lshl_add_u64 v[94:95], v[94:95], 0, v[248:249]
	s_waitcnt lgkmcnt(4)
	global_store_dwordx4 v[94:95], v[244:247], off
	s_waitcnt lgkmcnt(0)
	global_store_dwordx4 v[94:95], v[82:85], off offset:256
	s_nop 1
	v_mov_b32_e32 v82, v0
	s_nop 1
	v_permlane16_swap_b32_e32 v0, v82
	v_add_f32_e32 v0, v0, v82
	v_mov_b32_e32 v82, v0
	s_nop 1
	v_permlane32_swap_b32_e32 v0, v82
	s_and_saveexec_b64 s[12:13], s[4:5]
	s_cbranch_execz .LBB0_1092
	v_lshlrev_b64 v[84:85], 6, v[228:229]
	v_lshl_add_u64 v[84:85], v[204:205], 0, v[84:85]
	v_lshl_add_u64 v[84:85], s[8:9], 1, v[84:85]
	s_lshl_b32 s28, s23, 1
	s_mov_b32 s29, s40
	v_lshl_add_u64 v[84:85], v[84:85], 0, s[28:29]
	v_add_f32_e32 v0, v0, v82
	v_cvt_pk_bf16_f32 v0, v0, v1
	global_store_short v[84:85], v0, off
.LBB0_1092:
	s_or_b64 exec, exec, s[12:13]
	v_lshlrev_b32_e32 v84, 16, v166
	v_and_b32_e32 v85, 0xffff0000, v166
	v_lshlrev_b32_e32 v86, 16, v167
	v_and_b32_e32 v87, 0xffff0000, v167
	v_lshlrev_b32_e32 v88, 16, v168
	v_and_b32_e32 v89, 0xffff0000, v168
	v_lshlrev_b32_e32 v90, 16, v169
	v_and_b32_e32 v91, 0xffff0000, v169
	v_pk_add_f32 v[80:81], v[80:81], v[86:87]
	v_pk_add_f32 v[78:79], v[78:79], v[84:85]
	v_pk_add_f32 v[84:85], v[76:77], v[90:91]
	v_pk_add_f32 v[76:77], v[74:75], v[88:89]
	v_mul_f32_e32 v0, v79, v79
	v_mul_f32_e32 v74, v81, v81
	v_fmac_f32_e32 v0, v78, v78
	v_fmac_f32_e32 v74, v80, v80
	v_add_f32_e32 v0, v0, v74
	v_mul_f32_e32 v74, v77, v77
	v_mul_f32_e32 v75, v85, v85
	v_fmac_f32_e32 v74, v76, v76
	v_fmac_f32_e32 v75, v84, v84
	v_lshlrev_b64 v[82:83], 11, v[226:227]
	v_add_f32_e32 v74, v74, v75
	v_add_f32_e32 v0, v0, v74
	v_cvt_pk_bf16_f32 v74, v78, v79
	v_lshl_add_u64 v[78:79], v[82:83], 1, v[202:203]
	v_cvt_pk_bf16_f32 v75, v80, v81
	v_cvt_pk_bf16_f32 v76, v76, v77
	v_cvt_pk_bf16_f32 v77, v84, v85
	v_lshl_add_u64 v[78:79], v[216:217], 1, v[78:79]
	ds_bpermute_b32 v244, v255, v74
	ds_bpermute_b32 v245, v255, v75
	ds_bpermute_b32 v246, v255, v76
	ds_bpermute_b32 v247, v255, v77
	v_lshlrev_b32_e32 v80, 16, v164
	v_and_b32_e32 v81, 0xffff0000, v164
	v_lshlrev_b32_e32 v74, 16, v162
	v_and_b32_e32 v75, 0xffff0000, v162
	v_lshlrev_b32_e32 v76, 16, v163
	v_and_b32_e32 v77, 0xffff0000, v163
	v_lshlrev_b32_e32 v82, 16, v165
	v_and_b32_e32 v83, 0xffff0000, v165
	v_pk_add_f32 v[72:73], v[72:73], v[76:77]
	v_pk_add_f32 v[70:71], v[70:71], v[74:75]
	v_pk_add_f32 v[74:75], v[68:69], v[82:83]
	v_pk_add_f32 v[68:69], v[66:67], v[80:81]
	v_mul_f32_e32 v66, v71, v71
	v_mul_f32_e32 v67, v73, v73
	v_fmac_f32_e32 v66, v70, v70
	v_fmac_f32_e32 v67, v72, v72
	v_add_f32_e32 v66, v66, v67
	v_mul_f32_e32 v67, v69, v69
	v_mul_f32_e32 v76, v75, v75
	v_fmac_f32_e32 v67, v68, v68
	v_fmac_f32_e32 v76, v74, v74
	v_add_f32_e32 v67, v67, v76
	v_add_f32_e32 v66, v66, v67
	v_add_f32_e32 v0, v0, v66
	v_cvt_pk_bf16_f32 v66, v70, v71
	v_cvt_pk_bf16_f32 v67, v72, v73
	v_cvt_pk_bf16_f32 v68, v68, v69
	v_cvt_pk_bf16_f32 v69, v74, v75
	ds_bpermute_b32 v66, v255, v66
	ds_bpermute_b32 v67, v255, v67
	ds_bpermute_b32 v68, v255, v68
	ds_bpermute_b32 v69, v255, v69
	v_lshl_add_u64 v[78:79], v[78:79], 0, v[248:249]
	s_waitcnt lgkmcnt(4)
	global_store_dwordx4 v[78:79], v[244:247], off
	s_waitcnt lgkmcnt(0)
	global_store_dwordx4 v[78:79], v[66:69], off offset:256
	s_nop 1
	v_mov_b32_e32 v66, v0
	s_nop 1
	v_permlane16_swap_b32_e32 v0, v66
	v_add_f32_e32 v0, v0, v66
	v_mov_b32_e32 v66, v0
	s_nop 1
	v_permlane32_swap_b32_e32 v0, v66
	s_and_saveexec_b64 s[12:13], s[4:5]
	s_cbranch_execz .LBB0_1094
	v_lshlrev_b64 v[68:69], 6, v[226:227]
	v_lshl_add_u64 v[68:69], v[204:205], 0, v[68:69]
	v_lshl_add_u64 v[68:69], s[8:9], 1, v[68:69]
	s_lshl_b32 s28, s23, 1
	s_mov_b32 s29, s40
	v_lshl_add_u64 v[68:69], v[68:69], 0, s[28:29]
	v_add_f32_e32 v0, v0, v66
	v_cvt_pk_bf16_f32 v0, v0, v1
	global_store_short v[68:69], v0, off
.LBB0_1094:
	s_or_b64 exec, exec, s[12:13]
	v_lshlrev_b32_e32 v68, 16, v158
	v_and_b32_e32 v69, 0xffff0000, v158
	v_lshlrev_b32_e32 v70, 16, v159
	v_and_b32_e32 v71, 0xffff0000, v159
	v_lshlrev_b32_e32 v72, 16, v160
	v_and_b32_e32 v73, 0xffff0000, v160
	v_lshlrev_b32_e32 v74, 16, v161
	v_and_b32_e32 v75, 0xffff0000, v161
	v_pk_add_f32 v[64:65], v[64:65], v[70:71]
	v_pk_add_f32 v[62:63], v[62:63], v[68:69]
	v_pk_add_f32 v[68:69], v[60:61], v[74:75]
	v_pk_add_f32 v[60:61], v[58:59], v[72:73]
	v_mul_f32_e32 v0, v63, v63
	v_mul_f32_e32 v58, v65, v65
	v_fmac_f32_e32 v0, v62, v62
	v_fmac_f32_e32 v58, v64, v64
	v_add_f32_e32 v0, v0, v58
	v_mul_f32_e32 v58, v61, v61
	v_mul_f32_e32 v59, v69, v69
	v_fmac_f32_e32 v58, v60, v60
	v_fmac_f32_e32 v59, v68, v68
	v_lshlrev_b64 v[66:67], 11, v[224:225]
	v_add_f32_e32 v58, v58, v59
	v_add_f32_e32 v0, v0, v58
	v_cvt_pk_bf16_f32 v58, v62, v63
	v_lshl_add_u64 v[62:63], v[66:67], 1, v[202:203]
	v_cvt_pk_bf16_f32 v59, v64, v65
	v_cvt_pk_bf16_f32 v60, v60, v61
	v_cvt_pk_bf16_f32 v61, v68, v69
	v_lshl_add_u64 v[62:63], v[216:217], 1, v[62:63]
	ds_bpermute_b32 v244, v255, v58
	ds_bpermute_b32 v245, v255, v59
	ds_bpermute_b32 v246, v255, v60
	ds_bpermute_b32 v247, v255, v61
	v_lshlrev_b32_e32 v64, 16, v156
	v_and_b32_e32 v65, 0xffff0000, v156
	v_lshlrev_b32_e32 v58, 16, v154
	v_and_b32_e32 v59, 0xffff0000, v154
	v_lshlrev_b32_e32 v60, 16, v155
	v_and_b32_e32 v61, 0xffff0000, v155
	v_lshlrev_b32_e32 v66, 16, v157
	v_and_b32_e32 v67, 0xffff0000, v157
	v_pk_add_f32 v[56:57], v[56:57], v[60:61]
	v_pk_add_f32 v[54:55], v[54:55], v[58:59]
	v_pk_add_f32 v[58:59], v[52:53], v[66:67]
	v_pk_add_f32 v[52:53], v[50:51], v[64:65]
	v_mul_f32_e32 v50, v55, v55
	v_mul_f32_e32 v51, v57, v57
	v_fmac_f32_e32 v50, v54, v54
	v_fmac_f32_e32 v51, v56, v56
	v_add_f32_e32 v50, v50, v51
	v_mul_f32_e32 v51, v53, v53
	v_mul_f32_e32 v60, v59, v59
	v_fmac_f32_e32 v51, v52, v52
	v_fmac_f32_e32 v60, v58, v58
	v_add_f32_e32 v51, v51, v60
	v_add_f32_e32 v50, v50, v51
	v_add_f32_e32 v0, v0, v50
	v_cvt_pk_bf16_f32 v50, v54, v55
	v_cvt_pk_bf16_f32 v51, v56, v57
	v_cvt_pk_bf16_f32 v52, v52, v53
	v_cvt_pk_bf16_f32 v53, v58, v59
	ds_bpermute_b32 v50, v255, v50
	ds_bpermute_b32 v51, v255, v51
	ds_bpermute_b32 v52, v255, v52
	ds_bpermute_b32 v53, v255, v53
	v_lshl_add_u64 v[62:63], v[62:63], 0, v[248:249]
	s_waitcnt lgkmcnt(4)
	global_store_dwordx4 v[62:63], v[244:247], off
	s_waitcnt lgkmcnt(0)
	global_store_dwordx4 v[62:63], v[50:53], off offset:256
	s_nop 1
	v_mov_b32_e32 v50, v0
	s_nop 1
	v_permlane16_swap_b32_e32 v0, v50
	v_add_f32_e32 v0, v0, v50
	v_mov_b32_e32 v50, v0
	s_nop 1
	v_permlane32_swap_b32_e32 v0, v50
	s_and_saveexec_b64 s[12:13], s[4:5]
	s_cbranch_execz .LBB0_1096
	v_lshlrev_b64 v[52:53], 6, v[224:225]
	v_lshl_add_u64 v[52:53], v[204:205], 0, v[52:53]
	v_lshl_add_u64 v[52:53], s[8:9], 1, v[52:53]
	s_lshl_b32 s28, s23, 1
	s_mov_b32 s29, s40
	v_lshl_add_u64 v[52:53], v[52:53], 0, s[28:29]
	v_add_f32_e32 v0, v0, v50
	v_cvt_pk_bf16_f32 v0, v0, v1
	global_store_short v[52:53], v0, off
.LBB0_1096:
	s_or_b64 exec, exec, s[12:13]
	v_lshlrev_b32_e32 v52, 16, v150
	v_and_b32_e32 v53, 0xffff0000, v150
	v_lshlrev_b32_e32 v54, 16, v151
	v_and_b32_e32 v55, 0xffff0000, v151
	v_lshlrev_b32_e32 v56, 16, v152
	v_and_b32_e32 v57, 0xffff0000, v152
	v_lshlrev_b32_e32 v58, 16, v153
	v_and_b32_e32 v59, 0xffff0000, v153
	v_pk_add_f32 v[48:49], v[48:49], v[54:55]
	v_pk_add_f32 v[46:47], v[46:47], v[52:53]
	v_pk_add_f32 v[52:53], v[44:45], v[58:59]
	v_pk_add_f32 v[44:45], v[42:43], v[56:57]
	v_mul_f32_e32 v0, v47, v47
	v_mul_f32_e32 v42, v49, v49
	v_fmac_f32_e32 v0, v46, v46
	v_fmac_f32_e32 v42, v48, v48
	v_add_f32_e32 v0, v0, v42
	v_mul_f32_e32 v42, v45, v45
	v_mul_f32_e32 v43, v53, v53
	v_fmac_f32_e32 v42, v44, v44
	v_fmac_f32_e32 v43, v52, v52
	v_lshlrev_b64 v[50:51], 11, v[222:223]
	v_add_f32_e32 v42, v42, v43
	v_add_f32_e32 v0, v0, v42
	v_cvt_pk_bf16_f32 v42, v46, v47
	v_lshl_add_u64 v[46:47], v[50:51], 1, v[202:203]
	v_cvt_pk_bf16_f32 v43, v48, v49
	v_cvt_pk_bf16_f32 v44, v44, v45
	v_cvt_pk_bf16_f32 v45, v52, v53
	v_lshl_add_u64 v[46:47], v[216:217], 1, v[46:47]
	ds_bpermute_b32 v244, v255, v42
	ds_bpermute_b32 v245, v255, v43
	ds_bpermute_b32 v246, v255, v44
	ds_bpermute_b32 v247, v255, v45
	v_lshlrev_b32_e32 v48, 16, v148
	v_and_b32_e32 v49, 0xffff0000, v148
	v_lshlrev_b32_e32 v42, 16, v146
	v_and_b32_e32 v43, 0xffff0000, v146
	v_lshlrev_b32_e32 v44, 16, v147
	v_and_b32_e32 v45, 0xffff0000, v147
	v_lshlrev_b32_e32 v50, 16, v149
	v_and_b32_e32 v51, 0xffff0000, v149
	v_pk_add_f32 v[40:41], v[40:41], v[44:45]
	v_pk_add_f32 v[38:39], v[38:39], v[42:43]
	v_pk_add_f32 v[42:43], v[36:37], v[50:51]
	v_pk_add_f32 v[36:37], v[34:35], v[48:49]
	v_mul_f32_e32 v34, v39, v39
	v_mul_f32_e32 v35, v41, v41
	v_fmac_f32_e32 v34, v38, v38
	v_fmac_f32_e32 v35, v40, v40
	v_add_f32_e32 v34, v34, v35
	v_mul_f32_e32 v35, v37, v37
	v_mul_f32_e32 v44, v43, v43
	v_fmac_f32_e32 v35, v36, v36
	v_fmac_f32_e32 v44, v42, v42
	v_add_f32_e32 v35, v35, v44
	v_add_f32_e32 v34, v34, v35
	v_add_f32_e32 v0, v0, v34
	v_cvt_pk_bf16_f32 v34, v38, v39
	v_cvt_pk_bf16_f32 v35, v40, v41
	v_cvt_pk_bf16_f32 v36, v36, v37
	v_cvt_pk_bf16_f32 v37, v42, v43
	ds_bpermute_b32 v34, v255, v34
	ds_bpermute_b32 v35, v255, v35
	ds_bpermute_b32 v36, v255, v36
	ds_bpermute_b32 v37, v255, v37
	v_lshl_add_u64 v[46:47], v[46:47], 0, v[248:249]
	s_waitcnt lgkmcnt(4)
	global_store_dwordx4 v[46:47], v[244:247], off
	s_waitcnt lgkmcnt(0)
	global_store_dwordx4 v[46:47], v[34:37], off offset:256
	s_nop 1
	v_mov_b32_e32 v34, v0
	s_nop 1
	v_permlane16_swap_b32_e32 v0, v34
	v_add_f32_e32 v0, v0, v34
	v_mov_b32_e32 v34, v0
	s_nop 1
	v_permlane32_swap_b32_e32 v0, v34
	s_and_saveexec_b64 s[12:13], s[4:5]
	s_cbranch_execz .LBB0_1098
	v_lshlrev_b64 v[36:37], 6, v[222:223]
	v_lshl_add_u64 v[36:37], v[204:205], 0, v[36:37]
	v_lshl_add_u64 v[36:37], s[8:9], 1, v[36:37]
	s_lshl_b32 s28, s23, 1
	s_mov_b32 s29, s40
	v_lshl_add_u64 v[36:37], v[36:37], 0, s[28:29]
	v_add_f32_e32 v0, v0, v34
	v_cvt_pk_bf16_f32 v0, v0, v1
	global_store_short v[36:37], v0, off
.LBB0_1098:
	s_or_b64 exec, exec, s[12:13]
	v_lshlrev_b32_e32 v36, 16, v138
	v_and_b32_e32 v37, 0xffff0000, v138
	v_lshlrev_b32_e32 v38, 16, v139
	v_and_b32_e32 v39, 0xffff0000, v139
	v_lshlrev_b32_e32 v40, 16, v140
	v_and_b32_e32 v41, 0xffff0000, v140
	v_lshlrev_b32_e32 v42, 16, v141
	v_and_b32_e32 v43, 0xffff0000, v141
	v_pk_add_f32 v[32:33], v[32:33], v[38:39]
	v_pk_add_f32 v[30:31], v[30:31], v[36:37]
	v_pk_add_f32 v[36:37], v[28:29], v[42:43]
	v_pk_add_f32 v[28:29], v[26:27], v[40:41]
	v_mul_f32_e32 v0, v31, v31
	v_mul_f32_e32 v26, v33, v33
	v_fmac_f32_e32 v0, v30, v30
	v_fmac_f32_e32 v26, v32, v32
	v_add_f32_e32 v0, v0, v26
	v_mul_f32_e32 v26, v29, v29
	v_mul_f32_e32 v27, v37, v37
	v_fmac_f32_e32 v26, v28, v28
	v_fmac_f32_e32 v27, v36, v36
	v_lshlrev_b64 v[34:35], 11, v[220:221]
	v_add_f32_e32 v26, v26, v27
	v_add_f32_e32 v0, v0, v26
	v_cvt_pk_bf16_f32 v26, v30, v31
	v_lshl_add_u64 v[30:31], v[34:35], 1, v[202:203]
	v_cvt_pk_bf16_f32 v27, v32, v33
	v_cvt_pk_bf16_f32 v28, v28, v29
	v_cvt_pk_bf16_f32 v29, v36, v37
	v_lshl_add_u64 v[30:31], v[216:217], 1, v[30:31]
	ds_bpermute_b32 v244, v255, v26
	ds_bpermute_b32 v245, v255, v27
	ds_bpermute_b32 v246, v255, v28
	ds_bpermute_b32 v247, v255, v29
	v_lshlrev_b32_e32 v32, 16, v132
	v_and_b32_e32 v33, 0xffff0000, v132
	v_lshlrev_b32_e32 v26, 16, v130
	v_and_b32_e32 v27, 0xffff0000, v130
	v_lshlrev_b32_e32 v28, 16, v131
	v_and_b32_e32 v29, 0xffff0000, v131
	v_lshlrev_b32_e32 v34, 16, v133
	v_and_b32_e32 v35, 0xffff0000, v133
	v_pk_add_f32 v[24:25], v[24:25], v[28:29]
	v_pk_add_f32 v[22:23], v[22:23], v[26:27]
	v_pk_add_f32 v[26:27], v[20:21], v[34:35]
	v_pk_add_f32 v[20:21], v[18:19], v[32:33]
	v_mul_f32_e32 v18, v23, v23
	v_mul_f32_e32 v19, v25, v25
	v_fmac_f32_e32 v18, v22, v22
	v_fmac_f32_e32 v19, v24, v24
	v_add_f32_e32 v18, v18, v19
	v_mul_f32_e32 v19, v21, v21
	v_mul_f32_e32 v28, v27, v27
	v_fmac_f32_e32 v19, v20, v20
	v_fmac_f32_e32 v28, v26, v26
	v_add_f32_e32 v19, v19, v28
	v_add_f32_e32 v18, v18, v19
	v_add_f32_e32 v0, v0, v18
	v_cvt_pk_bf16_f32 v18, v22, v23
	v_cvt_pk_bf16_f32 v19, v24, v25
	v_cvt_pk_bf16_f32 v20, v20, v21
	v_cvt_pk_bf16_f32 v21, v26, v27
	ds_bpermute_b32 v18, v255, v18
	ds_bpermute_b32 v19, v255, v19
	ds_bpermute_b32 v20, v255, v20
	ds_bpermute_b32 v21, v255, v21
	v_lshl_add_u64 v[30:31], v[30:31], 0, v[248:249]
	s_waitcnt lgkmcnt(4)
	global_store_dwordx4 v[30:31], v[244:247], off
	s_waitcnt lgkmcnt(0)
	global_store_dwordx4 v[30:31], v[18:21], off offset:256
	s_nop 1
	v_mov_b32_e32 v18, v0
	s_nop 1
	v_permlane16_swap_b32_e32 v0, v18
	v_add_f32_e32 v0, v0, v18
	v_mov_b32_e32 v18, v0
	s_nop 1
	v_permlane32_swap_b32_e32 v0, v18
	s_and_saveexec_b64 s[12:13], s[4:5]
	s_cbranch_execz .LBB0_1100
	v_lshlrev_b64 v[20:21], 6, v[220:221]
	v_lshl_add_u64 v[20:21], v[204:205], 0, v[20:21]
	v_lshl_add_u64 v[20:21], s[8:9], 1, v[20:21]
	s_lshl_b32 s28, s23, 1
	s_mov_b32 s29, s40
	v_lshl_add_u64 v[20:21], v[20:21], 0, s[28:29]
	v_add_f32_e32 v0, v0, v18
	v_cvt_pk_bf16_f32 v0, v0, v1
	global_store_short v[20:21], v0, off
.LBB0_1100:
	s_or_b64 exec, exec, s[12:13]
	v_lshlrev_b32_e32 v20, 16, v142
	v_and_b32_e32 v21, 0xffff0000, v142
	v_lshlrev_b32_e32 v22, 16, v143
	v_and_b32_e32 v23, 0xffff0000, v143
	v_lshlrev_b32_e32 v24, 16, v144
	v_and_b32_e32 v25, 0xffff0000, v144
	v_lshlrev_b32_e32 v26, 16, v145
	v_and_b32_e32 v27, 0xffff0000, v145
	v_pk_add_f32 v[16:17], v[16:17], v[22:23]
	v_pk_add_f32 v[14:15], v[14:15], v[20:21]
	v_pk_add_f32 v[20:21], v[12:13], v[26:27]
	v_pk_add_f32 v[12:13], v[10:11], v[24:25]
	v_mul_f32_e32 v0, v15, v15
	v_mul_f32_e32 v10, v17, v17
	v_fmac_f32_e32 v0, v14, v14
	v_fmac_f32_e32 v10, v16, v16
	v_add_f32_e32 v0, v0, v10
	v_mul_f32_e32 v10, v13, v13
	v_mul_f32_e32 v11, v21, v21
	v_fmac_f32_e32 v10, v12, v12
	v_fmac_f32_e32 v11, v20, v20
	v_lshlrev_b64 v[18:19], 11, v[218:219]
	v_add_f32_e32 v10, v10, v11
	v_add_f32_e32 v0, v0, v10
	v_cvt_pk_bf16_f32 v10, v14, v15
	v_lshl_add_u64 v[14:15], v[18:19], 1, v[202:203]
	v_cvt_pk_bf16_f32 v11, v16, v17
	v_cvt_pk_bf16_f32 v12, v12, v13
	v_cvt_pk_bf16_f32 v13, v20, v21
	v_lshl_add_u64 v[14:15], v[216:217], 1, v[14:15]
	ds_bpermute_b32 v244, v255, v10
	ds_bpermute_b32 v245, v255, v11
	ds_bpermute_b32 v246, v255, v12
	ds_bpermute_b32 v247, v255, v13
	v_lshlrev_b32_e32 v16, 16, v136
	v_and_b32_e32 v17, 0xffff0000, v136
	v_lshlrev_b32_e32 v10, 16, v134
	v_and_b32_e32 v11, 0xffff0000, v134
	v_lshlrev_b32_e32 v12, 16, v135
	v_and_b32_e32 v13, 0xffff0000, v135
	v_lshlrev_b32_e32 v18, 16, v137
	v_and_b32_e32 v19, 0xffff0000, v137
	v_pk_add_f32 v[8:9], v[8:9], v[12:13]
	v_pk_add_f32 v[6:7], v[6:7], v[10:11]
	v_pk_add_f32 v[10:11], v[4:5], v[18:19]
	v_pk_add_f32 v[4:5], v[2:3], v[16:17]
	v_mul_f32_e32 v2, v7, v7
	v_mul_f32_e32 v3, v9, v9
	v_fmac_f32_e32 v2, v6, v6
	v_fmac_f32_e32 v3, v8, v8
	v_add_f32_e32 v2, v2, v3
	v_mul_f32_e32 v3, v5, v5
	v_mul_f32_e32 v12, v11, v11
	v_fmac_f32_e32 v3, v4, v4
	v_fmac_f32_e32 v12, v10, v10
	v_add_f32_e32 v3, v3, v12
	v_add_f32_e32 v2, v2, v3
	v_add_f32_e32 v0, v0, v2
	v_cvt_pk_bf16_f32 v2, v6, v7
	v_cvt_pk_bf16_f32 v3, v8, v9
	v_cvt_pk_bf16_f32 v4, v4, v5
	v_cvt_pk_bf16_f32 v5, v10, v11
	ds_bpermute_b32 v2, v255, v2
	ds_bpermute_b32 v3, v255, v3
	ds_bpermute_b32 v4, v255, v4
	ds_bpermute_b32 v5, v255, v5
	v_lshl_add_u64 v[14:15], v[14:15], 0, v[248:249]
	s_waitcnt lgkmcnt(4)
	global_store_dwordx4 v[14:15], v[244:247], off
	s_waitcnt lgkmcnt(0)
	global_store_dwordx4 v[14:15], v[2:5], off offset:256
	s_nop 1
	v_mov_b32_e32 v2, v0
	s_nop 1
	v_permlane16_swap_b32_e32 v0, v2
	v_add_f32_e32 v0, v0, v2
	v_mov_b32_e32 v2, v0
	s_nop 1
	v_permlane32_swap_b32_e32 v0, v2
	s_and_saveexec_b64 s[12:13], s[4:5]
	s_cbranch_execz .LBB0_1102
	v_lshlrev_b64 v[4:5], 6, v[218:219]
	v_lshl_add_u64 v[4:5], v[204:205], 0, v[4:5]
	v_lshl_add_u64 v[4:5], s[8:9], 1, v[4:5]
	s_lshl_b32 s8, s23, 1
	s_mov_b32 s9, s40
	v_lshl_add_u64 v[4:5], v[4:5], 0, s[8:9]
	v_add_f32_e32 v0, v0, v2
	v_cvt_pk_bf16_f32 v0, v0, v1
	global_store_short v[4:5], v0, off

.LBB0_1237:
	v_mbcnt_lo_u32_b32 v255, -1, 0
	v_mbcnt_hi_u32_b32 v255, -1, v255
	v_lshrrev_b32_e32 v244, 2, v255
	v_and_b32_e32 v245, 3, v255
	v_and_b32_e32 v246, 15, v255
	v_lshrrev_b32_e32 v247, 4, v255
	v_sub_u32_e32 v246, v244, v246
	v_sub_u32_e32 v247, v245, v247
	v_mul_i32_i24_e32 v246, 0x1000, v246
	v_lshl_add_u32 v248, v247, 4, v246
	v_ashrrev_i32_e32 v249, 31, v248
	v_lshl_add_u32 v255, v245, 4, v244
	v_lshlrev_b32_e32 v255, 2, v255
	v_lshl_or_b32 v218, s12, 8, v252
	v_lshl_add_u32 v234, s14, 8, v250
	v_ashrrev_i32_e32 v219, 31, v218
	v_lshlrev_b64 v[236:237], 1, v[218:219]
	v_ashrrev_i32_e32 v235, 31, v234
	v_lshl_add_u64 v[138:139], v[200:201], 0, v[236:237]
	v_lshlrev_b64 v[238:239], 12, v[234:235]
	v_lshl_add_u64 v[134:135], v[138:139], 0, v[238:239]
	global_load_dwordx4 v[194:197], v[134:135], off
	global_load_dwordx4 v[190:193], v[134:135], off offset:256
	v_or_b32_e32 v232, 16, v234
	v_ashrrev_i32_e32 v233, 31, v232
	v_lshlrev_b64 v[134:135], 12, v[232:233]
	v_or_b32_e32 v230, 32, v234
	v_lshl_add_u64 v[134:135], v[138:139], 0, v[134:135]
	v_ashrrev_i32_e32 v231, 31, v230
	global_load_dwordx4 v[186:189], v[134:135], off
	global_load_dwordx4 v[182:185], v[134:135], off offset:256
	v_lshlrev_b64 v[134:135], 12, v[230:231]
	v_or_b32_e32 v228, 48, v234
	v_lshl_add_u64 v[134:135], v[138:139], 0, v[134:135]
	v_ashrrev_i32_e32 v229, 31, v228
	global_load_dwordx4 v[178:181], v[134:135], off
	global_load_dwordx4 v[174:177], v[134:135], off offset:256
	v_lshlrev_b64 v[134:135], 12, v[228:229]
	v_add_u32_e32 v226, 0x80, v234
	v_lshl_add_u64 v[134:135], v[138:139], 0, v[134:135]
	v_ashrrev_i32_e32 v227, 31, v226
	global_load_dwordx4 v[170:173], v[134:135], off
	global_load_dwordx4 v[166:169], v[134:135], off offset:256
	v_lshlrev_b64 v[134:135], 12, v[226:227]
	v_add_u32_e32 v224, 0x90, v234
	v_lshl_add_u64 v[134:135], v[138:139], 0, v[134:135]
	v_ashrrev_i32_e32 v225, 31, v224
	global_load_dwordx4 v[162:165], v[134:135], off
	global_load_dwordx4 v[158:161], v[134:135], off offset:256
	v_lshlrev_b64 v[134:135], 12, v[224:225]
	v_add_u32_e32 v222, 0xa0, v234
	v_add_u32_e32 v220, 0xb0, v234
	v_lshl_add_u64 v[134:135], v[138:139], 0, v[134:135]
	v_ashrrev_i32_e32 v223, 31, v222
	v_ashrrev_i32_e32 v221, 31, v220
	global_load_dwordx4 v[154:157], v[134:135], off
	global_load_dwordx4 v[150:153], v[134:135], off offset:256
	v_lshlrev_b64 v[134:135], 12, v[222:223]
	v_lshlrev_b64 v[140:141], 12, v[220:221]
	v_lshl_add_u64 v[134:135], v[138:139], 0, v[134:135]
	v_lshl_add_u64 v[138:139], v[138:139], 0, v[140:141]
	global_load_dwordx4 v[142:145], v[134:135], off
	s_nop 0
	global_load_dwordx4 v[134:137], v[134:135], off offset:256
	s_nop 0
	global_load_dwordx4 v[146:149], v[138:139], off
	s_nop 0
	global_load_dwordx4 v[138:141], v[138:139], off offset:256
	s_mov_b64 vcc, s[2:3]
	s_cbranch_vccz .Lalign_skip_5
	s_barrier
.Lalign_skip_5:
	s_lshl_b32 s12, s12, 2
	s_ashr_i32 s13, s12, 31
	s_waitcnt vmcnt(0)
	v_lshlrev_b32_e32 v206, 16, v194
	v_and_b32_e32 v207, 0xffff0000, v194
	v_lshlrev_b32_e32 v194, 16, v195
	v_and_b32_e32 v195, 0xffff0000, v195
	v_pk_add_f32 v[128:129], v[128:129], v[194:195]
	v_pk_add_f32 v[126:127], v[126:127], v[206:207]
	v_lshlrev_b32_e32 v208, 16, v196
	v_and_b32_e32 v209, 0xffff0000, v196
	v_mul_f32_e32 v0, v127, v127
	v_mul_f32_e32 v194, v129, v129
	v_pk_add_f32 v[130:131], v[130:131], v[208:209]
	v_fmac_f32_e32 v0, v126, v126
	v_fmac_f32_e32 v194, v128, v128
	v_add_f32_e32 v0, v0, v194
	v_mul_f32_e32 v194, v131, v131
	v_lshlrev_b32_e32 v196, 16, v197
	v_and_b32_e32 v197, 0xffff0000, v197
	v_fmac_f32_e32 v194, v130, v130
	v_cvt_pk_bf16_f32 v126, v126, v127
	v_cvt_pk_bf16_f32 v127, v128, v129
	v_cvt_pk_bf16_f32 v128, v130, v131
	v_lshl_add_u64 v[130:131], v[200:201], 0, v[238:239]
	v_pk_add_f32 v[132:133], v[132:133], v[196:197]
	v_lshl_add_u64 v[130:131], v[130:131], 0, v[236:237]
	v_cvt_pk_bf16_f32 v129, v132, v133
	v_mul_f32_e32 v195, v133, v133
	ds_bpermute_b32 v244, v255, v126
	ds_bpermute_b32 v245, v255, v127
	ds_bpermute_b32 v246, v255, v128
	ds_bpermute_b32 v247, v255, v129
	v_fmac_f32_e32 v195, v132, v132
	v_lshlrev_b32_e32 v132, 16, v192
	v_lshlrev_b32_e32 v126, 16, v190
	v_and_b32_e32 v127, 0xffff0000, v190
	v_lshlrev_b32_e32 v128, 16, v191
	v_and_b32_e32 v129, 0xffff0000, v191
	v_and_b32_e32 v133, 0xffff0000, v192
	v_lshlrev_b32_e32 v190, 16, v193
	v_and_b32_e32 v191, 0xffff0000, v193
	v_pk_add_f32 v[124:125], v[124:125], v[128:129]
	v_pk_add_f32 v[122:123], v[122:123], v[126:127]
	v_pk_add_f32 v[126:127], v[120:121], v[190:191]
	v_pk_add_f32 v[120:121], v[118:119], v[132:133]
	v_mul_f32_e32 v118, v123, v123
	v_mul_f32_e32 v119, v125, v125
	v_fmac_f32_e32 v118, v122, v122
	v_fmac_f32_e32 v119, v124, v124
	v_add_f32_e32 v118, v118, v119
	v_mul_f32_e32 v119, v121, v121
	v_mul_f32_e32 v128, v127, v127
	v_fmac_f32_e32 v119, v120, v120
	v_fmac_f32_e32 v128, v126, v126
	v_add_f32_e32 v194, v194, v195
	v_add_f32_e32 v119, v119, v128
	v_add_f32_e32 v0, v0, v194
	v_add_f32_e32 v118, v118, v119
	v_add_f32_e32 v0, v0, v118
	v_cvt_pk_bf16_f32 v118, v122, v123
	v_cvt_pk_bf16_f32 v119, v124, v125
	v_cvt_pk_bf16_f32 v120, v120, v121
	v_cvt_pk_bf16_f32 v121, v126, v127
	ds_bpermute_b32 v118, v255, v118
	ds_bpermute_b32 v119, v255, v119
	ds_bpermute_b32 v120, v255, v120
	ds_bpermute_b32 v121, v255, v121
	v_lshl_add_u64 v[130:131], v[130:131], 0, v[248:249]
	s_waitcnt lgkmcnt(4)
	global_store_dwordx4 v[130:131], v[244:247], off
	s_waitcnt lgkmcnt(0)
	global_store_dwordx4 v[130:131], v[118:121], off offset:256
	s_nop 1
	v_mov_b32_e32 v118, v0
	s_nop 1
	v_permlane16_swap_b32_e32 v0, v118
	v_add_f32_e32 v0, v0, v118
	v_mov_b32_e32 v118, v0
	s_nop 1
	v_permlane32_swap_b32_e32 v0, v118
	s_and_saveexec_b64 s[14:15], s[4:5]
	s_cbranch_execz .LBB0_1239
	v_lshlrev_b64 v[120:121], 6, v[234:235]
	v_lshl_add_u64 v[120:121], v[4:5], 0, v[120:121]
	v_lshl_add_u64 v[120:121], s[12:13], 1, v[120:121]
	s_lshl_b32 s16, s27, 1
	s_mov_b32 s17, s40
	v_lshl_add_u64 v[120:121], v[120:121], 0, s[16:17]
	v_add_f32_e32 v0, v0, v118
	v_cvt_pk_bf16_f32 v0, v0, v1
	global_store_short v[120:121], v0, off
.LBB0_1239:
	s_or_b64 exec, exec, s[14:15]
	v_lshlrev_b32_e32 v120, 16, v186
	v_and_b32_e32 v121, 0xffff0000, v186
	v_lshlrev_b32_e32 v122, 16, v187
	v_and_b32_e32 v123, 0xffff0000, v187
	v_lshlrev_b32_e32 v124, 16, v188
	v_and_b32_e32 v125, 0xffff0000, v188
	v_lshlrev_b32_e32 v126, 16, v189
	v_and_b32_e32 v127, 0xffff0000, v189
	v_pk_add_f32 v[116:117], v[116:117], v[122:123]
	v_pk_add_f32 v[114:115], v[114:115], v[120:121]
	v_pk_add_f32 v[120:121], v[112:113], v[126:127]
	v_pk_add_f32 v[112:113], v[110:111], v[124:125]
	v_mul_f32_e32 v0, v115, v115
	v_mul_f32_e32 v110, v117, v117
	v_fmac_f32_e32 v0, v114, v114
	v_fmac_f32_e32 v110, v116, v116
	v_add_f32_e32 v0, v0, v110
	v_mul_f32_e32 v110, v113, v113
	v_mul_f32_e32 v111, v121, v121
	v_fmac_f32_e32 v110, v112, v112
	v_fmac_f32_e32 v111, v120, v120
	v_lshlrev_b64 v[118:119], 11, v[232:233]
	v_add_f32_e32 v110, v110, v111
	v_add_f32_e32 v0, v0, v110
	v_cvt_pk_bf16_f32 v110, v114, v115
	v_lshl_add_u64 v[114:115], v[118:119], 1, v[200:201]
	v_cvt_pk_bf16_f32 v111, v116, v117
	v_cvt_pk_bf16_f32 v112, v112, v113
	v_cvt_pk_bf16_f32 v113, v120, v121
	v_lshl_add_u64 v[114:115], v[218:219], 1, v[114:115]
	ds_bpermute_b32 v244, v255, v110
	ds_bpermute_b32 v245, v255, v111
	ds_bpermute_b32 v246, v255, v112
	ds_bpermute_b32 v247, v255, v113
	v_lshlrev_b32_e32 v116, 16, v184
	v_and_b32_e32 v117, 0xffff0000, v184
	v_lshlrev_b32_e32 v110, 16, v182
	v_and_b32_e32 v111, 0xffff0000, v182
	v_lshlrev_b32_e32 v112, 16, v183
	v_and_b32_e32 v113, 0xffff0000, v183
	v_lshlrev_b32_e32 v118, 16, v185
	v_and_b32_e32 v119, 0xffff0000, v185
	v_pk_add_f32 v[108:109], v[108:109], v[112:113]
	v_pk_add_f32 v[106:107], v[106:107], v[110:111]
	v_pk_add_f32 v[110:111], v[104:105], v[118:119]
	v_pk_add_f32 v[104:105], v[102:103], v[116:117]
	v_mul_f32_e32 v102, v107, v107
	v_mul_f32_e32 v103, v109, v109
	v_fmac_f32_e32 v102, v106, v106
	v_fmac_f32_e32 v103, v108, v108
	v_add_f32_e32 v102, v102, v103
	v_mul_f32_e32 v103, v105, v105
	v_mul_f32_e32 v112, v111, v111
	v_fmac_f32_e32 v103, v104, v104
	v_fmac_f32_e32 v112, v110, v110
	v_add_f32_e32 v103, v103, v112
	v_add_f32_e32 v102, v102, v103
	v_add_f32_e32 v0, v0, v102
	v_cvt_pk_bf16_f32 v102, v106, v107
	v_cvt_pk_bf16_f32 v103, v108, v109
	v_cvt_pk_bf16_f32 v104, v104, v105
	v_cvt_pk_bf16_f32 v105, v110, v111
	ds_bpermute_b32 v102, v255, v102
	ds_bpermute_b32 v103, v255, v103
	ds_bpermute_b32 v104, v255, v104
	ds_bpermute_b32 v105, v255, v105
	v_lshl_add_u64 v[114:115], v[114:115], 0, v[248:249]
	s_waitcnt lgkmcnt(4)
	global_store_dwordx4 v[114:115], v[244:247], off
	s_waitcnt lgkmcnt(0)
	global_store_dwordx4 v[114:115], v[102:105], off offset:256
	s_nop 1
	v_mov_b32_e32 v102, v0
	s_nop 1
	v_permlane16_swap_b32_e32 v0, v102
	v_add_f32_e32 v0, v0, v102
	v_mov_b32_e32 v102, v0
	s_nop 1
	v_permlane32_swap_b32_e32 v0, v102
	s_and_saveexec_b64 s[14:15], s[4:5]
	s_cbranch_execz .LBB0_1241
	v_lshlrev_b64 v[104:105], 6, v[232:233]
	v_lshl_add_u64 v[104:105], v[4:5], 0, v[104:105]
	v_lshl_add_u64 v[104:105], s[12:13], 1, v[104:105]
	s_lshl_b32 s16, s27, 1
	s_mov_b32 s17, s40
	v_lshl_add_u64 v[104:105], v[104:105], 0, s[16:17]
	v_add_f32_e32 v0, v0, v102
	v_cvt_pk_bf16_f32 v0, v0, v1
	global_store_short v[104:105], v0, off
.LBB0_1241:
	s_or_b64 exec, exec, s[14:15]
	v_lshlrev_b32_e32 v104, 16, v178
	v_and_b32_e32 v105, 0xffff0000, v178
	v_lshlrev_b32_e32 v106, 16, v179
	v_and_b32_e32 v107, 0xffff0000, v179
	v_lshlrev_b32_e32 v108, 16, v180
	v_and_b32_e32 v109, 0xffff0000, v180
	v_lshlrev_b32_e32 v110, 16, v181
	v_and_b32_e32 v111, 0xffff0000, v181
	v_pk_add_f32 v[100:101], v[100:101], v[106:107]
	v_pk_add_f32 v[98:99], v[98:99], v[104:105]
	v_pk_add_f32 v[104:105], v[96:97], v[110:111]
	v_pk_add_f32 v[96:97], v[94:95], v[108:109]
	v_mul_f32_e32 v0, v99, v99
	v_mul_f32_e32 v94, v101, v101
	v_fmac_f32_e32 v0, v98, v98
	v_fmac_f32_e32 v94, v100, v100
	v_add_f32_e32 v0, v0, v94
	v_mul_f32_e32 v94, v97, v97
	v_mul_f32_e32 v95, v105, v105
	v_fmac_f32_e32 v94, v96, v96
	v_fmac_f32_e32 v95, v104, v104
	v_lshlrev_b64 v[102:103], 11, v[230:231]
	v_add_f32_e32 v94, v94, v95
	v_add_f32_e32 v0, v0, v94
	v_cvt_pk_bf16_f32 v94, v98, v99
	v_lshl_add_u64 v[98:99], v[102:103], 1, v[200:201]
	v_cvt_pk_bf16_f32 v95, v100, v101
	v_cvt_pk_bf16_f32 v96, v96, v97
	v_cvt_pk_bf16_f32 v97, v104, v105
	v_lshl_add_u64 v[98:99], v[218:219], 1, v[98:99]
	ds_bpermute_b32 v244, v255, v94
	ds_bpermute_b32 v245, v255, v95
	ds_bpermute_b32 v246, v255, v96
	ds_bpermute_b32 v247, v255, v97
	v_lshlrev_b32_e32 v100, 16, v176
	v_and_b32_e32 v101, 0xffff0000, v176
	v_lshlrev_b32_e32 v94, 16, v174
	v_and_b32_e32 v95, 0xffff0000, v174
	v_lshlrev_b32_e32 v96, 16, v175
	v_and_b32_e32 v97, 0xffff0000, v175
	v_lshlrev_b32_e32 v102, 16, v177
	v_and_b32_e32 v103, 0xffff0000, v177
	v_pk_add_f32 v[92:93], v[92:93], v[96:97]
	v_pk_add_f32 v[90:91], v[90:91], v[94:95]
	v_pk_add_f32 v[94:95], v[88:89], v[102:103]
	v_pk_add_f32 v[88:89], v[86:87], v[100:101]
	v_mul_f32_e32 v86, v91, v91
	v_mul_f32_e32 v87, v93, v93
	v_fmac_f32_e32 v86, v90, v90
	v_fmac_f32_e32 v87, v92, v92
	v_add_f32_e32 v86, v86, v87
	v_mul_f32_e32 v87, v89, v89
	v_mul_f32_e32 v96, v95, v95
	v_fmac_f32_e32 v87, v88, v88
	v_fmac_f32_e32 v96, v94, v94
	v_add_f32_e32 v87, v87, v96
	v_add_f32_e32 v86, v86, v87
	v_add_f32_e32 v0, v0, v86
	v_cvt_pk_bf16_f32 v86, v90, v91
	v_cvt_pk_bf16_f32 v87, v92, v93
	v_cvt_pk_bf16_f32 v88, v88, v89
	v_cvt_pk_bf16_f32 v89, v94, v95
	ds_bpermute_b32 v86, v255, v86
	ds_bpermute_b32 v87, v255, v87
	ds_bpermute_b32 v88, v255, v88
	ds_bpermute_b32 v89, v255, v89
	v_lshl_add_u64 v[98:99], v[98:99], 0, v[248:249]
	s_waitcnt lgkmcnt(4)
	global_store_dwordx4 v[98:99], v[244:247], off
	s_waitcnt lgkmcnt(0)
	global_store_dwordx4 v[98:99], v[86:89], off offset:256
	s_nop 1
	v_mov_b32_e32 v86, v0
	s_nop 1
	v_permlane16_swap_b32_e32 v0, v86
	v_add_f32_e32 v0, v0, v86
	v_mov_b32_e32 v86, v0
	s_nop 1
	v_permlane32_swap_b32_e32 v0, v86
	s_and_saveexec_b64 s[14:15], s[4:5]
	s_cbranch_execz .LBB0_1243
	v_lshlrev_b64 v[88:89], 6, v[230:231]
	v_lshl_add_u64 v[88:89], v[4:5], 0, v[88:89]
	v_lshl_add_u64 v[88:89], s[12:13], 1, v[88:89]
	s_lshl_b32 s16, s27, 1
	s_mov_b32 s17, s40
	v_lshl_add_u64 v[88:89], v[88:89], 0, s[16:17]
	v_add_f32_e32 v0, v0, v86
	v_cvt_pk_bf16_f32 v0, v0, v1
	global_store_short v[88:89], v0, off
.LBB0_1243:
	s_or_b64 exec, exec, s[14:15]
	v_lshlrev_b32_e32 v88, 16, v170
	v_and_b32_e32 v89, 0xffff0000, v170
	v_lshlrev_b32_e32 v90, 16, v171
	v_and_b32_e32 v91, 0xffff0000, v171
	v_lshlrev_b32_e32 v92, 16, v172
	v_and_b32_e32 v93, 0xffff0000, v172
	v_lshlrev_b32_e32 v94, 16, v173
	v_and_b32_e32 v95, 0xffff0000, v173
	v_pk_add_f32 v[84:85], v[84:85], v[90:91]
	v_pk_add_f32 v[82:83], v[82:83], v[88:89]
	v_pk_add_f32 v[88:89], v[80:81], v[94:95]
	v_pk_add_f32 v[80:81], v[78:79], v[92:93]
	v_mul_f32_e32 v0, v83, v83
	v_mul_f32_e32 v78, v85, v85
	v_fmac_f32_e32 v0, v82, v82
	v_fmac_f32_e32 v78, v84, v84
	v_add_f32_e32 v0, v0, v78
	v_mul_f32_e32 v78, v81, v81
	v_mul_f32_e32 v79, v89, v89
	v_fmac_f32_e32 v78, v80, v80
	v_fmac_f32_e32 v79, v88, v88
	v_lshlrev_b64 v[86:87], 11, v[228:229]
	v_add_f32_e32 v78, v78, v79
	v_add_f32_e32 v0, v0, v78
	v_cvt_pk_bf16_f32 v78, v82, v83
	v_lshl_add_u64 v[82:83], v[86:87], 1, v[200:201]
	v_cvt_pk_bf16_f32 v79, v84, v85
	v_cvt_pk_bf16_f32 v80, v80, v81
	v_cvt_pk_bf16_f32 v81, v88, v89
	v_lshl_add_u64 v[82:83], v[218:219], 1, v[82:83]
	ds_bpermute_b32 v244, v255, v78
	ds_bpermute_b32 v245, v255, v79
	ds_bpermute_b32 v246, v255, v80
	ds_bpermute_b32 v247, v255, v81
	v_lshlrev_b32_e32 v84, 16, v168
	v_and_b32_e32 v85, 0xffff0000, v168
	v_lshlrev_b32_e32 v78, 16, v166
	v_and_b32_e32 v79, 0xffff0000, v166
	v_lshlrev_b32_e32 v80, 16, v167
	v_and_b32_e32 v81, 0xffff0000, v167
	v_lshlrev_b32_e32 v86, 16, v169
	v_and_b32_e32 v87, 0xffff0000, v169
	v_pk_add_f32 v[76:77], v[76:77], v[80:81]
	v_pk_add_f32 v[74:75], v[74:75], v[78:79]
	v_pk_add_f32 v[78:79], v[72:73], v[86:87]
	v_pk_add_f32 v[72:73], v[70:71], v[84:85]
	v_mul_f32_e32 v70, v75, v75
	v_mul_f32_e32 v71, v77, v77
	v_fmac_f32_e32 v70, v74, v74
	v_fmac_f32_e32 v71, v76, v76
	v_add_f32_e32 v70, v70, v71
	v_mul_f32_e32 v71, v73, v73
	v_mul_f32_e32 v80, v79, v79
	v_fmac_f32_e32 v71, v72, v72
	v_fmac_f32_e32 v80, v78, v78
	v_add_f32_e32 v71, v71, v80
	v_add_f32_e32 v70, v70, v71
	v_add_f32_e32 v0, v0, v70
	v_cvt_pk_bf16_f32 v70, v74, v75
	v_cvt_pk_bf16_f32 v71, v76, v77
	v_cvt_pk_bf16_f32 v72, v72, v73
	v_cvt_pk_bf16_f32 v73, v78, v79
	ds_bpermute_b32 v70, v255, v70
	ds_bpermute_b32 v71, v255, v71
	ds_bpermute_b32 v72, v255, v72
	ds_bpermute_b32 v73, v255, v73
	v_lshl_add_u64 v[82:83], v[82:83], 0, v[248:249]
	s_waitcnt lgkmcnt(4)
	global_store_dwordx4 v[82:83], v[244:247], off
	s_waitcnt lgkmcnt(0)
	global_store_dwordx4 v[82:83], v[70:73], off offset:256
	s_nop 1
	v_mov_b32_e32 v70, v0
	s_nop 1
	v_permlane16_swap_b32_e32 v0, v70
	v_add_f32_e32 v0, v0, v70
	v_mov_b32_e32 v70, v0
	s_nop 1
	v_permlane32_swap_b32_e32 v0, v70
	s_and_saveexec_b64 s[14:15], s[4:5]
	s_cbranch_execz .LBB0_1245
	v_lshlrev_b64 v[72:73], 6, v[228:229]
	v_lshl_add_u64 v[72:73], v[4:5], 0, v[72:73]
	v_lshl_add_u64 v[72:73], s[12:13], 1, v[72:73]
	s_lshl_b32 s16, s27, 1
	s_mov_b32 s17, s40
	v_lshl_add_u64 v[72:73], v[72:73], 0, s[16:17]
	v_add_f32_e32 v0, v0, v70
	v_cvt_pk_bf16_f32 v0, v0, v1
	global_store_short v[72:73], v0, off
.LBB0_1245:
	s_or_b64 exec, exec, s[14:15]
	v_lshlrev_b32_e32 v72, 16, v162
	v_and_b32_e32 v73, 0xffff0000, v162
	v_lshlrev_b32_e32 v74, 16, v163
	v_and_b32_e32 v75, 0xffff0000, v163
	v_lshlrev_b32_e32 v76, 16, v164
	v_and_b32_e32 v77, 0xffff0000, v164
	v_lshlrev_b32_e32 v78, 16, v165
	v_and_b32_e32 v79, 0xffff0000, v165
	v_pk_add_f32 v[68:69], v[68:69], v[74:75]
	v_pk_add_f32 v[66:67], v[66:67], v[72:73]
	v_pk_add_f32 v[72:73], v[64:65], v[78:79]
	v_pk_add_f32 v[64:65], v[62:63], v[76:77]
	v_mul_f32_e32 v0, v67, v67
	v_mul_f32_e32 v62, v69, v69
	v_fmac_f32_e32 v0, v66, v66
	v_fmac_f32_e32 v62, v68, v68
	v_add_f32_e32 v0, v0, v62
	v_mul_f32_e32 v62, v65, v65
	v_mul_f32_e32 v63, v73, v73
	v_fmac_f32_e32 v62, v64, v64
	v_fmac_f32_e32 v63, v72, v72
	v_lshlrev_b64 v[70:71], 11, v[226:227]
	v_add_f32_e32 v62, v62, v63
	v_add_f32_e32 v0, v0, v62
	v_cvt_pk_bf16_f32 v62, v66, v67
	v_lshl_add_u64 v[66:67], v[70:71], 1, v[200:201]
	v_cvt_pk_bf16_f32 v63, v68, v69
	v_cvt_pk_bf16_f32 v64, v64, v65
	v_cvt_pk_bf16_f32 v65, v72, v73
	v_lshl_add_u64 v[66:67], v[218:219], 1, v[66:67]
	ds_bpermute_b32 v244, v255, v62
	ds_bpermute_b32 v245, v255, v63
	ds_bpermute_b32 v246, v255, v64
	ds_bpermute_b32 v247, v255, v65
	v_lshlrev_b32_e32 v68, 16, v160
	v_and_b32_e32 v69, 0xffff0000, v160
	v_lshlrev_b32_e32 v62, 16, v158
	v_and_b32_e32 v63, 0xffff0000, v158
	v_lshlrev_b32_e32 v64, 16, v159
	v_and_b32_e32 v65, 0xffff0000, v159
	v_lshlrev_b32_e32 v70, 16, v161
	v_and_b32_e32 v71, 0xffff0000, v161
	v_pk_add_f32 v[60:61], v[60:61], v[64:65]
	v_pk_add_f32 v[58:59], v[58:59], v[62:63]
	v_pk_add_f32 v[62:63], v[56:57], v[70:71]
	v_pk_add_f32 v[56:57], v[54:55], v[68:69]
	v_mul_f32_e32 v54, v59, v59
	v_mul_f32_e32 v55, v61, v61
	v_fmac_f32_e32 v54, v58, v58
	v_fmac_f32_e32 v55, v60, v60
	v_add_f32_e32 v54, v54, v55
	v_mul_f32_e32 v55, v57, v57
	v_mul_f32_e32 v64, v63, v63
	v_fmac_f32_e32 v55, v56, v56
	v_fmac_f32_e32 v64, v62, v62
	v_add_f32_e32 v55, v55, v64
	v_add_f32_e32 v54, v54, v55
	v_add_f32_e32 v0, v0, v54
	v_cvt_pk_bf16_f32 v54, v58, v59
	v_cvt_pk_bf16_f32 v55, v60, v61
	v_cvt_pk_bf16_f32 v56, v56, v57
	v_cvt_pk_bf16_f32 v57, v62, v63
	ds_bpermute_b32 v54, v255, v54
	ds_bpermute_b32 v55, v255, v55
	ds_bpermute_b32 v56, v255, v56
	ds_bpermute_b32 v57, v255, v57
	v_lshl_add_u64 v[66:67], v[66:67], 0, v[248:249]
	s_waitcnt lgkmcnt(4)
	global_store_dwordx4 v[66:67], v[244:247], off
	s_waitcnt lgkmcnt(0)
	global_store_dwordx4 v[66:67], v[54:57], off offset:256
	s_nop 1
	v_mov_b32_e32 v54, v0
	s_nop 1
	v_permlane16_swap_b32_e32 v0, v54
	v_add_f32_e32 v0, v0, v54
	v_mov_b32_e32 v54, v0
	s_nop 1
	v_permlane32_swap_b32_e32 v0, v54
	s_and_saveexec_b64 s[14:15], s[4:5]
	s_cbranch_execz .LBB0_1247
	v_lshlrev_b64 v[56:57], 6, v[226:227]
	v_lshl_add_u64 v[56:57], v[4:5], 0, v[56:57]
	v_lshl_add_u64 v[56:57], s[12:13], 1, v[56:57]
	s_lshl_b32 s16, s27, 1
	s_mov_b32 s17, s40
	v_lshl_add_u64 v[56:57], v[56:57], 0, s[16:17]
	v_add_f32_e32 v0, v0, v54
	v_cvt_pk_bf16_f32 v0, v0, v1
	global_store_short v[56:57], v0, off
.LBB0_1247:
	s_or_b64 exec, exec, s[14:15]
	v_lshlrev_b32_e32 v56, 16, v154
	v_and_b32_e32 v57, 0xffff0000, v154
	v_lshlrev_b32_e32 v58, 16, v155
	v_and_b32_e32 v59, 0xffff0000, v155
	v_lshlrev_b32_e32 v60, 16, v156
	v_and_b32_e32 v61, 0xffff0000, v156
	v_lshlrev_b32_e32 v62, 16, v157
	v_and_b32_e32 v63, 0xffff0000, v157
	v_pk_add_f32 v[52:53], v[52:53], v[58:59]
	v_pk_add_f32 v[50:51], v[50:51], v[56:57]
	v_pk_add_f32 v[56:57], v[48:49], v[62:63]
	v_pk_add_f32 v[48:49], v[46:47], v[60:61]
	v_mul_f32_e32 v0, v51, v51
	v_mul_f32_e32 v46, v53, v53
	v_fmac_f32_e32 v0, v50, v50
	v_fmac_f32_e32 v46, v52, v52
	v_add_f32_e32 v0, v0, v46
	v_mul_f32_e32 v46, v49, v49
	v_mul_f32_e32 v47, v57, v57
	v_fmac_f32_e32 v46, v48, v48
	v_fmac_f32_e32 v47, v56, v56
	v_lshlrev_b64 v[54:55], 11, v[224:225]
	v_add_f32_e32 v46, v46, v47
	v_add_f32_e32 v0, v0, v46
	v_cvt_pk_bf16_f32 v46, v50, v51
	v_lshl_add_u64 v[50:51], v[54:55], 1, v[200:201]
	v_cvt_pk_bf16_f32 v47, v52, v53
	v_cvt_pk_bf16_f32 v48, v48, v49
	v_cvt_pk_bf16_f32 v49, v56, v57
	v_lshl_add_u64 v[50:51], v[218:219], 1, v[50:51]
	ds_bpermute_b32 v244, v255, v46
	ds_bpermute_b32 v245, v255, v47
	ds_bpermute_b32 v246, v255, v48
	ds_bpermute_b32 v247, v255, v49
	v_lshlrev_b32_e32 v52, 16, v152
	v_and_b32_e32 v53, 0xffff0000, v152
	v_lshlrev_b32_e32 v46, 16, v150
	v_and_b32_e32 v47, 0xffff0000, v150
	v_lshlrev_b32_e32 v48, 16, v151
	v_and_b32_e32 v49, 0xffff0000, v151
	v_lshlrev_b32_e32 v54, 16, v153
	v_and_b32_e32 v55, 0xffff0000, v153
	v_pk_add_f32 v[44:45], v[44:45], v[48:49]
	v_pk_add_f32 v[42:43], v[42:43], v[46:47]
	v_pk_add_f32 v[46:47], v[40:41], v[54:55]
	v_pk_add_f32 v[40:41], v[38:39], v[52:53]
	v_mul_f32_e32 v38, v43, v43
	v_mul_f32_e32 v39, v45, v45
	v_fmac_f32_e32 v38, v42, v42
	v_fmac_f32_e32 v39, v44, v44
	v_add_f32_e32 v38, v38, v39
	v_mul_f32_e32 v39, v41, v41
	v_mul_f32_e32 v48, v47, v47
	v_fmac_f32_e32 v39, v40, v40
	v_fmac_f32_e32 v48, v46, v46
	v_add_f32_e32 v39, v39, v48
	v_add_f32_e32 v38, v38, v39
	v_add_f32_e32 v0, v0, v38
	v_cvt_pk_bf16_f32 v38, v42, v43
	v_cvt_pk_bf16_f32 v39, v44, v45
	v_cvt_pk_bf16_f32 v40, v40, v41
	v_cvt_pk_bf16_f32 v41, v46, v47
	ds_bpermute_b32 v38, v255, v38
	ds_bpermute_b32 v39, v255, v39
	ds_bpermute_b32 v40, v255, v40
	ds_bpermute_b32 v41, v255, v41
	v_lshl_add_u64 v[50:51], v[50:51], 0, v[248:249]
	s_waitcnt lgkmcnt(4)
	global_store_dwordx4 v[50:51], v[244:247], off
	s_waitcnt lgkmcnt(0)
	global_store_dwordx4 v[50:51], v[38:41], off offset:256
	s_nop 1
	v_mov_b32_e32 v38, v0
	s_nop 1
	v_permlane16_swap_b32_e32 v0, v38
	v_add_f32_e32 v0, v0, v38
	v_mov_b32_e32 v38, v0
	s_nop 1
	v_permlane32_swap_b32_e32 v0, v38
	s_and_saveexec_b64 s[14:15], s[4:5]
	s_cbranch_execz .LBB0_1249
	v_lshlrev_b64 v[40:41], 6, v[224:225]
	v_lshl_add_u64 v[40:41], v[4:5], 0, v[40:41]
	v_lshl_add_u64 v[40:41], s[12:13], 1, v[40:41]
	s_lshl_b32 s16, s27, 1
	s_mov_b32 s17, s40
	v_lshl_add_u64 v[40:41], v[40:41], 0, s[16:17]
	v_add_f32_e32 v0, v0, v38
	v_cvt_pk_bf16_f32 v0, v0, v1
	global_store_short v[40:41], v0, off
.LBB0_1249:
	s_or_b64 exec, exec, s[14:15]
	v_lshlrev_b32_e32 v40, 16, v142
	v_and_b32_e32 v41, 0xffff0000, v142
	v_lshlrev_b32_e32 v42, 16, v143
	v_and_b32_e32 v43, 0xffff0000, v143
	v_lshlrev_b32_e32 v44, 16, v144
	v_and_b32_e32 v45, 0xffff0000, v144
	v_lshlrev_b32_e32 v46, 16, v145
	v_and_b32_e32 v47, 0xffff0000, v145
	v_pk_add_f32 v[36:37], v[36:37], v[42:43]
	v_pk_add_f32 v[34:35], v[34:35], v[40:41]
	v_pk_add_f32 v[40:41], v[32:33], v[46:47]
	v_pk_add_f32 v[32:33], v[30:31], v[44:45]
	v_mul_f32_e32 v0, v35, v35
	v_mul_f32_e32 v30, v37, v37
	v_fmac_f32_e32 v0, v34, v34
	v_fmac_f32_e32 v30, v36, v36
	v_add_f32_e32 v0, v0, v30
	v_mul_f32_e32 v30, v33, v33
	v_mul_f32_e32 v31, v41, v41
	v_fmac_f32_e32 v30, v32, v32
	v_fmac_f32_e32 v31, v40, v40
	v_lshlrev_b64 v[38:39], 11, v[222:223]
	v_add_f32_e32 v30, v30, v31
	v_add_f32_e32 v0, v0, v30
	v_cvt_pk_bf16_f32 v30, v34, v35
	v_lshl_add_u64 v[34:35], v[38:39], 1, v[200:201]
	v_cvt_pk_bf16_f32 v31, v36, v37
	v_cvt_pk_bf16_f32 v32, v32, v33
	v_cvt_pk_bf16_f32 v33, v40, v41
	v_lshl_add_u64 v[34:35], v[218:219], 1, v[34:35]
	ds_bpermute_b32 v244, v255, v30
	ds_bpermute_b32 v245, v255, v31
	ds_bpermute_b32 v246, v255, v32
	ds_bpermute_b32 v247, v255, v33
	v_lshlrev_b32_e32 v36, 16, v136
	v_and_b32_e32 v37, 0xffff0000, v136
	v_lshlrev_b32_e32 v30, 16, v134
	v_and_b32_e32 v31, 0xffff0000, v134
	v_lshlrev_b32_e32 v32, 16, v135
	v_and_b32_e32 v33, 0xffff0000, v135
	v_lshlrev_b32_e32 v38, 16, v137
	v_and_b32_e32 v39, 0xffff0000, v137
	v_pk_add_f32 v[28:29], v[28:29], v[32:33]
	v_pk_add_f32 v[26:27], v[26:27], v[30:31]
	v_pk_add_f32 v[30:31], v[24:25], v[38:39]
	v_pk_add_f32 v[24:25], v[22:23], v[36:37]
	v_mul_f32_e32 v22, v27, v27
	v_mul_f32_e32 v23, v29, v29
	v_fmac_f32_e32 v22, v26, v26
	v_fmac_f32_e32 v23, v28, v28
	v_add_f32_e32 v22, v22, v23
	v_mul_f32_e32 v23, v25, v25
	v_mul_f32_e32 v32, v31, v31
	v_fmac_f32_e32 v23, v24, v24
	v_fmac_f32_e32 v32, v30, v30
	v_add_f32_e32 v23, v23, v32
	v_add_f32_e32 v22, v22, v23
	v_add_f32_e32 v0, v0, v22
	v_cvt_pk_bf16_f32 v22, v26, v27
	v_cvt_pk_bf16_f32 v23, v28, v29
	v_cvt_pk_bf16_f32 v24, v24, v25
	v_cvt_pk_bf16_f32 v25, v30, v31
	ds_bpermute_b32 v22, v255, v22
	ds_bpermute_b32 v23, v255, v23
	ds_bpermute_b32 v24, v255, v24
	ds_bpermute_b32 v25, v255, v25
	v_lshl_add_u64 v[34:35], v[34:35], 0, v[248:249]
	s_waitcnt lgkmcnt(4)
	global_store_dwordx4 v[34:35], v[244:247], off
	s_waitcnt lgkmcnt(0)
	global_store_dwordx4 v[34:35], v[22:25], off offset:256
	s_nop 1
	v_mov_b32_e32 v22, v0
	s_nop 1
	v_permlane16_swap_b32_e32 v0, v22
	v_add_f32_e32 v0, v0, v22
	v_mov_b32_e32 v22, v0
	s_nop 1
	v_permlane32_swap_b32_e32 v0, v22
	s_and_saveexec_b64 s[14:15], s[4:5]
	s_cbranch_execz .LBB0_1251
	v_lshlrev_b64 v[24:25], 6, v[222:223]
	v_lshl_add_u64 v[24:25], v[4:5], 0, v[24:25]
	v_lshl_add_u64 v[24:25], s[12:13], 1, v[24:25]
	s_lshl_b32 s16, s27, 1
	s_mov_b32 s17, s40
	v_lshl_add_u64 v[24:25], v[24:25], 0, s[16:17]
	v_add_f32_e32 v0, v0, v22
	v_cvt_pk_bf16_f32 v0, v0, v1
	global_store_short v[24:25], v0, off
.LBB0_1251:
	s_or_b64 exec, exec, s[14:15]
	v_lshlrev_b32_e32 v24, 16, v146
	v_and_b32_e32 v25, 0xffff0000, v146
	v_lshlrev_b32_e32 v26, 16, v147
	v_and_b32_e32 v27, 0xffff0000, v147
	v_lshlrev_b32_e32 v28, 16, v148
	v_and_b32_e32 v29, 0xffff0000, v148
	v_lshlrev_b32_e32 v30, 16, v149
	v_and_b32_e32 v31, 0xffff0000, v149
	v_pk_add_f32 v[20:21], v[20:21], v[26:27]
	v_pk_add_f32 v[18:19], v[18:19], v[24:25]
	v_pk_add_f32 v[24:25], v[16:17], v[30:31]
	v_pk_add_f32 v[16:17], v[14:15], v[28:29]
	v_mul_f32_e32 v0, v19, v19
	v_mul_f32_e32 v14, v21, v21
	v_fmac_f32_e32 v0, v18, v18
	v_fmac_f32_e32 v14, v20, v20
	v_add_f32_e32 v0, v0, v14
	v_mul_f32_e32 v14, v17, v17
	v_mul_f32_e32 v15, v25, v25
	v_fmac_f32_e32 v14, v16, v16
	v_fmac_f32_e32 v15, v24, v24
	v_lshlrev_b64 v[22:23], 11, v[220:221]
	v_add_f32_e32 v14, v14, v15
	v_add_f32_e32 v0, v0, v14
	v_cvt_pk_bf16_f32 v14, v18, v19
	v_lshl_add_u64 v[18:19], v[22:23], 1, v[200:201]
	v_cvt_pk_bf16_f32 v15, v20, v21
	v_cvt_pk_bf16_f32 v16, v16, v17
	v_cvt_pk_bf16_f32 v17, v24, v25
	v_lshl_add_u64 v[18:19], v[218:219], 1, v[18:19]
	ds_bpermute_b32 v244, v255, v14
	ds_bpermute_b32 v245, v255, v15
	ds_bpermute_b32 v246, v255, v16
	ds_bpermute_b32 v247, v255, v17
	v_lshlrev_b32_e32 v20, 16, v140
	v_and_b32_e32 v21, 0xffff0000, v140
	v_lshlrev_b32_e32 v14, 16, v138
	v_and_b32_e32 v15, 0xffff0000, v138
	v_lshlrev_b32_e32 v16, 16, v139
	v_and_b32_e32 v17, 0xffff0000, v139
	v_lshlrev_b32_e32 v22, 16, v141
	v_and_b32_e32 v23, 0xffff0000, v141
	v_pk_add_f32 v[12:13], v[12:13], v[16:17]
	v_pk_add_f32 v[10:11], v[10:11], v[14:15]
	v_pk_add_f32 v[14:15], v[8:9], v[22:23]
	v_pk_add_f32 v[8:9], v[6:7], v[20:21]
	v_mul_f32_e32 v6, v11, v11
	v_mul_f32_e32 v7, v13, v13
	v_fmac_f32_e32 v6, v10, v10
	v_fmac_f32_e32 v7, v12, v12
	v_add_f32_e32 v6, v6, v7
	v_mul_f32_e32 v7, v9, v9
	v_mul_f32_e32 v16, v15, v15
	v_fmac_f32_e32 v7, v8, v8
	v_fmac_f32_e32 v16, v14, v14
	v_add_f32_e32 v7, v7, v16
	v_add_f32_e32 v6, v6, v7
	v_add_f32_e32 v0, v0, v6
	v_cvt_pk_bf16_f32 v6, v10, v11
	v_cvt_pk_bf16_f32 v7, v12, v13
	v_cvt_pk_bf16_f32 v8, v8, v9
	v_cvt_pk_bf16_f32 v9, v14, v15
	ds_bpermute_b32 v6, v255, v6
	ds_bpermute_b32 v7, v255, v7
	ds_bpermute_b32 v8, v255, v8
	ds_bpermute_b32 v9, v255, v9
	v_lshl_add_u64 v[18:19], v[18:19], 0, v[248:249]
	s_waitcnt lgkmcnt(4)
	global_store_dwordx4 v[18:19], v[244:247], off
	s_waitcnt lgkmcnt(0)
	global_store_dwordx4 v[18:19], v[6:9], off offset:256
	s_nop 1
	v_mov_b32_e32 v6, v0
	s_nop 1
	v_permlane16_swap_b32_e32 v0, v6
	v_add_f32_e32 v0, v0, v6
	v_mov_b32_e32 v6, v0
	s_nop 1
	v_permlane32_swap_b32_e32 v0, v6
	s_and_saveexec_b64 s[14:15], s[4:5]
	s_cbranch_execz .LBB0_1253
	v_lshlrev_b64 v[8:9], 6, v[220:221]
	v_lshl_add_u64 v[8:9], v[4:5], 0, v[8:9]
	v_lshl_add_u64 v[8:9], s[12:13], 1, v[8:9]
	s_lshl_b32 s12, s27, 1
	s_mov_b32 s13, s40
	v_lshl_add_u64 v[8:9], v[8:9], 0, s[12:13]
	v_add_f32_e32 v0, v0, v6
	v_cvt_pk_bf16_f32 v0, v0, v1
	global_store_short v[8:9], v0, off
